# nt cache hint on once-read streams: f32 weight reads of all transposes and of the adaLN GEMV, final-norm loads and stores
# speedup vs baseline: 1.0230x; 1.0230x over previous
.LBB0_15:
	v_add_co_u32_e64 v22, s[0:1], s20, v8
	v_mov_b32_e32 v102, s11
	s_nop 0
	v_addc_co_u32_e64 v23, s[0:1], -1, v9, s[0:1]
	v_add_co_u32_e64 v24, s[0:1], s21, v8
	global_load_dwordx2 v[20:21], v[8:9], off nt
	s_nop 0
	v_addc_co_u32_e64 v25, s[0:1], -1, v9, s[0:1]
	v_add_co_u32_e64 v26, s[0:1], s22, v8
	s_add_i32 s11, s11, 64
	s_nop 0
	v_addc_co_u32_e64 v27, s[0:1], -1, v9, s[0:1]
	v_add_co_u32_e64 v28, s[0:1], s23, v8
	s_add_i32 s10, s10, 16
	s_nop 0
	v_addc_co_u32_e64 v29, s[0:1], -1, v9, s[0:1]
	v_add_co_u32_e64 v30, s[0:1], s24, v8
	s_cmp_ge_i32 s10, s12
	s_nop 0
	v_addc_co_u32_e64 v31, s[0:1], -1, v9, s[0:1]
	v_add_co_u32_e64 v32, s[0:1], s25, v8
	s_nop 1
	v_addc_co_u32_e64 v33, s[0:1], -1, v9, s[0:1]
	v_add_co_u32_e64 v34, s[0:1], s26, v8
	s_nop 1
	v_addc_co_u32_e64 v35, s[0:1], -1, v9, s[0:1]
	v_add_co_u32_e64 v36, s[0:1], s27, v8
	global_load_dwordx2 v[106:107], v[22:23], off nt
	global_load_dwordx2 v[108:109], v[24:25], off nt
	global_load_dwordx2 v[110:111], v[26:27], off nt
	global_load_dwordx2 v[112:113], v[28:29], off nt
	global_load_dwordx2 v[114:115], v[30:31], off nt
	global_load_dwordx2 v[116:117], v[32:33], off nt
	global_load_dwordx2 v[118:119], v[34:35], off nt
	v_addc_co_u32_e64 v37, s[0:1], -1, v9, s[0:1]
	v_add_co_u32_e64 v38, s[0:1], s28, v8
	ds_read_b128 v[22:25], v102
	ds_read_b128 v[26:29], v102 offset:16
	ds_read_b128 v[30:33], v102 offset:8192
	ds_read_b128 v[46:49], v102 offset:8208
	v_addc_co_u32_e64 v39, s[0:1], -1, v9, s[0:1]
	v_add_co_u32_e64 v40, s[0:1], s29, v8
	global_load_dwordx2 v[120:121], v[36:37], off nt
	s_nop 0
	v_addc_co_u32_e64 v41, s[0:1], -1, v9, s[0:1]
	v_add_co_u32_e64 v70, s[0:1], s30, v8
	ds_read_b128 v[34:37], v102 offset:16384
	ds_read_b128 v[50:53], v102 offset:16400
	ds_read_b128 v[54:57], v102 offset:24576
	ds_read_b128 v[58:61], v102 offset:24592
	v_addc_co_u32_e64 v71, s[0:1], -1, v9, s[0:1]
	v_add_co_u32_e64 v72, s[0:1], s31, v8
	global_load_dwordx2 v[122:123], v[38:39], off nt
	s_nop 0
	v_addc_co_u32_e64 v73, s[0:1], -1, v9, s[0:1]
	v_add_co_u32_e64 v74, s[0:1], s36, v8
	ds_read_b128 v[62:65], v102 offset:32768
	ds_read_b128 v[66:69], v102 offset:32784
	v_addc_co_u32_e64 v75, s[0:1], -1, v9, s[0:1]
	v_add_co_u32_e64 v76, s[0:1], s37, v8
	s_waitcnt lgkmcnt(9)
	v_mov_b32_e32 v136, v25
	v_addc_co_u32_e64 v77, s[0:1], -1, v9, s[0:1]
	v_add_co_u32_e64 v78, s[0:1], s38, v8
	s_waitcnt lgkmcnt(7)
	v_mov_b32_e32 v138, v33
	v_addc_co_u32_e64 v79, s[0:1], -1, v9, s[0:1]
	global_load_dwordx2 v[124:125], v[40:41], off nt
	global_load_dwordx2 v[126:127], v[70:71], off nt
	global_load_dwordx2 v[128:129], v[72:73], off nt
	global_load_dwordx2 v[130:131], v[74:75], off nt
	global_load_dwordx2 v[132:133], v[76:77], off nt
	global_load_dwordx2 v[134:135], v[78:79], off nt
	s_waitcnt lgkmcnt(5)
	v_mov_b32_e32 v140, v37
	s_waitcnt lgkmcnt(3)
	v_mov_b32_e32 v142, v57
	s_waitcnt lgkmcnt(1)
	v_mov_b32_e32 v144, v65
	ds_read_b128 v[38:41], v102 offset:32
	ds_read_b128 v[70:73], v102 offset:48
	ds_read_b128 v[74:77], v102 offset:8224
	ds_read_b128 v[78:81], v102 offset:8240
	ds_read_b128 v[82:85], v102 offset:16416
	ds_read_b128 v[86:89], v102 offset:16432
	ds_read_b128 v[90:93], v102 offset:24608
	ds_read_b128 v[94:97], v102 offset:24624
	ds_read_b128 v[98:101], v102 offset:32800
	ds_read_b128 v[102:105], v102 offset:32816
	v_mov_b32_e32 v146, v29
	v_mov_b32_e32 v148, v49
	v_mov_b32_e32 v150, v53
	v_mov_b32_e32 v152, v61
	s_waitcnt lgkmcnt(10)
	v_mov_b32_e32 v154, v69
	s_waitcnt lgkmcnt(9)
	v_mov_b32_e32 v156, v41
	s_waitcnt lgkmcnt(7)
	v_mov_b32_e32 v160, v77
	s_waitcnt lgkmcnt(5)
	v_mov_b32_e32 v164, v85
	s_waitcnt lgkmcnt(3)
	v_mov_b32_e32 v168, v93
	s_waitcnt lgkmcnt(1)
	v_mov_b32_e32 v172, v101
	v_mov_b32_e32 v158, v73
	v_mov_b32_e32 v162, v81
	v_mov_b32_e32 v166, v89
	v_mov_b32_e32 v170, v97
	s_waitcnt lgkmcnt(0)
	v_mov_b32_e32 v174, v105
	v_lshl_add_u64 v[8:9], v[8:9], 0, s[6:7]
	s_waitcnt vmcnt(14)
	v_pk_fma_f32 v[18:19], v[106:107], v[22:23], v[18:19] op_sel_hi:[1,0,1]
	v_pk_fma_f32 v[16:17], v[106:107], v[30:31], v[16:17] op_sel_hi:[1,0,1]
	v_pk_fma_f32 v[14:15], v[106:107], v[34:35], v[14:15] op_sel_hi:[1,0,1]
	v_pk_fma_f32 v[12:13], v[106:107], v[54:55], v[12:13] op_sel_hi:[1,0,1]
	v_pk_fma_f32 v[10:11], v[106:107], v[62:63], v[10:11] op_sel_hi:[1,0,1]
	s_waitcnt vmcnt(13)
	v_pk_fma_f32 v[18:19], v[108:109], v[22:23], v[18:19] op_sel:[0,1,0]
	v_pk_fma_f32 v[16:17], v[108:109], v[30:31], v[16:17] op_sel:[0,1,0]
	v_pk_fma_f32 v[14:15], v[108:109], v[34:35], v[14:15] op_sel:[0,1,0]
	v_pk_fma_f32 v[12:13], v[108:109], v[54:55], v[12:13] op_sel:[0,1,0]
	v_pk_fma_f32 v[10:11], v[108:109], v[62:63], v[10:11] op_sel:[0,1,0]
	s_waitcnt vmcnt(12)
	v_pk_fma_f32 v[18:19], v[110:111], v[24:25], v[18:19] op_sel_hi:[1,0,1]
	v_pk_fma_f32 v[16:17], v[110:111], v[32:33], v[16:17] op_sel_hi:[1,0,1]
	v_pk_fma_f32 v[14:15], v[110:111], v[36:37], v[14:15] op_sel_hi:[1,0,1]
	v_pk_fma_f32 v[12:13], v[110:111], v[56:57], v[12:13] op_sel_hi:[1,0,1]
	v_pk_fma_f32 v[10:11], v[110:111], v[64:65], v[10:11] op_sel_hi:[1,0,1]
	s_waitcnt vmcnt(11)
	v_pk_fma_f32 v[18:19], v[112:113], v[136:137], v[18:19] op_sel_hi:[1,0,1]
	v_pk_fma_f32 v[16:17], v[112:113], v[138:139], v[16:17] op_sel_hi:[1,0,1]
	v_pk_fma_f32 v[14:15], v[112:113], v[140:141], v[14:15] op_sel_hi:[1,0,1]
	v_pk_fma_f32 v[12:13], v[112:113], v[142:143], v[12:13] op_sel_hi:[1,0,1]
	v_pk_fma_f32 v[10:11], v[112:113], v[144:145], v[10:11] op_sel_hi:[1,0,1]
	s_waitcnt vmcnt(10)
	v_pk_fma_f32 v[18:19], v[114:115], v[26:27], v[18:19] op_sel_hi:[1,0,1]
	v_pk_fma_f32 v[16:17], v[114:115], v[46:47], v[16:17] op_sel_hi:[1,0,1]
	v_pk_fma_f32 v[14:15], v[114:115], v[50:51], v[14:15] op_sel_hi:[1,0,1]
	v_pk_fma_f32 v[12:13], v[114:115], v[58:59], v[12:13] op_sel_hi:[1,0,1]
	v_pk_fma_f32 v[10:11], v[114:115], v[66:67], v[10:11] op_sel_hi:[1,0,1]
	s_waitcnt vmcnt(9)
	v_pk_fma_f32 v[18:19], v[116:117], v[26:27], v[18:19] op_sel:[0,1,0]
	v_pk_fma_f32 v[16:17], v[116:117], v[46:47], v[16:17] op_sel:[0,1,0]
	v_pk_fma_f32 v[14:15], v[116:117], v[50:51], v[14:15] op_sel:[0,1,0]
	v_pk_fma_f32 v[12:13], v[116:117], v[58:59], v[12:13] op_sel:[0,1,0]
	v_pk_fma_f32 v[10:11], v[116:117], v[66:67], v[10:11] op_sel:[0,1,0]
	s_waitcnt vmcnt(8)
	v_pk_fma_f32 v[18:19], v[118:119], v[28:29], v[18:19] op_sel_hi:[1,0,1]
	v_pk_fma_f32 v[16:17], v[118:119], v[48:49], v[16:17] op_sel_hi:[1,0,1]
	v_pk_fma_f32 v[14:15], v[118:119], v[52:53], v[14:15] op_sel_hi:[1,0,1]
	v_pk_fma_f32 v[12:13], v[118:119], v[60:61], v[12:13] op_sel_hi:[1,0,1]
	v_pk_fma_f32 v[10:11], v[118:119], v[68:69], v[10:11] op_sel_hi:[1,0,1]
	s_waitcnt vmcnt(7)
	v_pk_fma_f32 v[18:19], v[120:121], v[146:147], v[18:19] op_sel_hi:[1,0,1]
	v_pk_fma_f32 v[16:17], v[120:121], v[148:149], v[16:17] op_sel_hi:[1,0,1]
	v_pk_fma_f32 v[14:15], v[120:121], v[150:151], v[14:15] op_sel_hi:[1,0,1]
	v_pk_fma_f32 v[12:13], v[120:121], v[152:153], v[12:13] op_sel_hi:[1,0,1]
	v_pk_fma_f32 v[10:11], v[120:121], v[154:155], v[10:11] op_sel_hi:[1,0,1]
	s_waitcnt vmcnt(6)
	v_pk_fma_f32 v[18:19], v[122:123], v[38:39], v[18:19] op_sel_hi:[1,0,1]
	v_pk_fma_f32 v[16:17], v[122:123], v[74:75], v[16:17] op_sel_hi:[1,0,1]
	v_pk_fma_f32 v[14:15], v[122:123], v[82:83], v[14:15] op_sel_hi:[1,0,1]
	v_pk_fma_f32 v[12:13], v[122:123], v[90:91], v[12:13] op_sel_hi:[1,0,1]
	v_pk_fma_f32 v[10:11], v[122:123], v[98:99], v[10:11] op_sel_hi:[1,0,1]
	s_waitcnt vmcnt(5)
	v_pk_fma_f32 v[18:19], v[124:125], v[38:39], v[18:19] op_sel:[0,1,0]
	v_pk_fma_f32 v[16:17], v[124:125], v[74:75], v[16:17] op_sel:[0,1,0]
	v_pk_fma_f32 v[14:15], v[124:125], v[82:83], v[14:15] op_sel:[0,1,0]
	v_pk_fma_f32 v[12:13], v[124:125], v[90:91], v[12:13] op_sel:[0,1,0]
	v_pk_fma_f32 v[10:11], v[124:125], v[98:99], v[10:11] op_sel:[0,1,0]
	s_waitcnt vmcnt(4)
	v_pk_fma_f32 v[18:19], v[126:127], v[40:41], v[18:19] op_sel_hi:[1,0,1]
	v_pk_fma_f32 v[16:17], v[126:127], v[76:77], v[16:17] op_sel_hi:[1,0,1]
	v_pk_fma_f32 v[14:15], v[126:127], v[84:85], v[14:15] op_sel_hi:[1,0,1]
	v_pk_fma_f32 v[12:13], v[126:127], v[92:93], v[12:13] op_sel_hi:[1,0,1]
	v_pk_fma_f32 v[10:11], v[126:127], v[100:101], v[10:11] op_sel_hi:[1,0,1]
	s_waitcnt vmcnt(3)
	v_pk_fma_f32 v[18:19], v[128:129], v[156:157], v[18:19] op_sel_hi:[1,0,1]
	v_pk_fma_f32 v[16:17], v[128:129], v[160:161], v[16:17] op_sel_hi:[1,0,1]
	v_pk_fma_f32 v[14:15], v[128:129], v[164:165], v[14:15] op_sel_hi:[1,0,1]
	v_pk_fma_f32 v[12:13], v[128:129], v[168:169], v[12:13] op_sel_hi:[1,0,1]
	v_pk_fma_f32 v[10:11], v[128:129], v[172:173], v[10:11] op_sel_hi:[1,0,1]
	s_waitcnt vmcnt(2)
	v_pk_fma_f32 v[18:19], v[130:131], v[70:71], v[18:19] op_sel_hi:[1,0,1]
	v_pk_fma_f32 v[16:17], v[130:131], v[78:79], v[16:17] op_sel_hi:[1,0,1]
	v_pk_fma_f32 v[14:15], v[130:131], v[86:87], v[14:15] op_sel_hi:[1,0,1]
	v_pk_fma_f32 v[12:13], v[130:131], v[94:95], v[12:13] op_sel_hi:[1,0,1]
	v_pk_fma_f32 v[10:11], v[130:131], v[102:103], v[10:11] op_sel_hi:[1,0,1]
	s_waitcnt vmcnt(1)
	v_pk_fma_f32 v[18:19], v[132:133], v[70:71], v[18:19] op_sel:[0,1,0]
	v_pk_fma_f32 v[16:17], v[132:133], v[78:79], v[16:17] op_sel:[0,1,0]
	v_pk_fma_f32 v[14:15], v[132:133], v[86:87], v[14:15] op_sel:[0,1,0]
	v_pk_fma_f32 v[12:13], v[132:133], v[94:95], v[12:13] op_sel:[0,1,0]
	v_pk_fma_f32 v[10:11], v[132:133], v[102:103], v[10:11] op_sel:[0,1,0]
	s_waitcnt vmcnt(0)
	v_pk_fma_f32 v[18:19], v[134:135], v[72:73], v[18:19] op_sel_hi:[1,0,1]
	v_pk_fma_f32 v[16:17], v[134:135], v[80:81], v[16:17] op_sel_hi:[1,0,1]
	v_pk_fma_f32 v[14:15], v[134:135], v[88:89], v[14:15] op_sel_hi:[1,0,1]
	v_pk_fma_f32 v[12:13], v[134:135], v[96:97], v[12:13] op_sel_hi:[1,0,1]
	v_pk_fma_f32 v[10:11], v[134:135], v[104:105], v[10:11] op_sel_hi:[1,0,1]
	v_pk_fma_f32 v[18:19], v[20:21], v[158:159], v[18:19] op_sel_hi:[1,0,1]
	v_pk_fma_f32 v[16:17], v[20:21], v[162:163], v[16:17] op_sel_hi:[1,0,1]
	v_pk_fma_f32 v[14:15], v[20:21], v[166:167], v[14:15] op_sel_hi:[1,0,1]
	v_pk_fma_f32 v[12:13], v[20:21], v[170:171], v[12:13] op_sel_hi:[1,0,1]
	v_pk_fma_f32 v[10:11], v[20:21], v[174:175], v[10:11] op_sel_hi:[1,0,1]
	s_cbranch_scc0 .LBB0_15
	ds_write2st64_b64 v44, v[18:19], v[16:17] offset0:80 offset1:81
	ds_write2st64_b64 v44, v[14:15], v[12:13] offset0:82 offset1:83
	ds_write_b64 v44, v[10:11] offset:43008
	s_waitcnt lgkmcnt(0)
	s_barrier
	s_and_saveexec_b64 s[10:11], vcc
	s_cbranch_execz .LBB0_13
	s_mul_i32 s0, s9, 0x3000
	s_add_i32 s0, s0, s8
	v_or_b32_e32 v8, s0, v45
	s_mul_i32 s40, s9, 5
	s_ashr_i32 s9, s8, 31
	v_ashrrev_i32_e32 v9, 31, v8
	v_lshl_add_u64 v[8:9], v[8:9], 2, s[46:47]
	v_lshl_add_u64 v[10:11], s[8:9], 2, v[6:7]
	s_mov_b64 s[8:9], 0
	v_mov_b32_e32 v12, v42
.LBB0_18:
	global_load_dword v13, v[8:9], off nt
	v_and_b32_e32 v15, 0x3fffff80, v12
	v_ashrrev_i32_e32 v14, 7, v12
	v_add_u32_e32 v16, 0x200, v12
	v_lshl_add_u32 v20, v15, 2, v4
	v_cmp_lt_i32_e64 s[0:1], s13, v12
	v_add_u32_e32 v22, s40, v14
	v_mov_b32_e32 v12, v16
	ds_read2st64_b32 v[14:15], v20 offset0:160 offset1:170
	ds_read2st64_b32 v[16:17], v20 offset0:180 offset1:190
	ds_read2st64_b32 v[18:19], v20 offset0:200 offset1:210
	ds_read2st64_b32 v[20:21], v20 offset0:220 offset1:230
	s_or_b64 s[8:9], s[0:1], s[8:9]
	s_waitcnt lgkmcnt(3)
	v_add_f32_e32 v14, 0, v14
	v_add_f32_e32 v14, v14, v15
	s_waitcnt lgkmcnt(2)
	v_add_f32_e32 v14, v14, v16
	v_add_f32_e32 v14, v14, v17
	s_waitcnt lgkmcnt(1)
	v_add_f32_e32 v14, v14, v18
	v_add_f32_e32 v14, v14, v19
	s_waitcnt lgkmcnt(0)
	v_add_f32_e32 v14, v14, v20
	v_add_f32_e32 v14, v14, v21
	v_mad_i64_i32 v[22:23], s[0:1], v22, s17, v[10:11]
	s_waitcnt vmcnt(0)
	v_add_f32_e32 v13, v14, v13
	global_store_dword v[22:23], v13, off
	s_andn2_b64 exec, exec, s[8:9]
	s_cbranch_execnz .LBB0_18
	s_branch .LBB0_13

.LBB0_22:
	s_mul_hi_i32 s0, s10, 0x5e6ea9af
	s_lshr_b32 s1, s0, 31
	s_ashr_i32 s0, s0, 13
	s_add_i32 s0, s0, s1
	s_mul_i32 s1, s0, 0xffffa940
	s_add_i32 s58, s10, s1
	s_ashr_i32 s1, s0, 31
	s_mul_i32 s7, s0, 0x5780000
	s_mul_hi_i32 s6, s0, 0x5780000
	s_add_u32 s56, s12, s7
	s_addc_u32 s57, s13, s6
	s_cmpk_gt_i32 s58, 0xb3f
	s_mov_b64 s[6:7], -1
	s_cbranch_scc0 .LBB0_40
	s_cmpk_gt_u32 s58, 0xcbf
	s_cbranch_scc0 .LBB0_37
	s_cmpk_gt_u32 s58, 0xebf
	s_cbranch_scc0 .LBB0_34
	s_cmpk_gt_u32 s58, 0x16bf
	s_cbranch_scc0 .LBB0_31
	s_lshl_b64 s[6:7], s[0:1], 26
	s_cmpk_gt_u32 s58, 0x36bf
	s_mov_b64 s[8:9], -1
	s_cbranch_scc0 .LBB0_28
	v_readlane_b32 s68, v248, 18
	v_readlane_b32 s78, v248, 28
	v_readlane_b32 s79, v248, 29
	s_add_u32 s59, s78, s6
	s_addc_u32 s61, s79, s7
	s_add_i32 s8, s58, 0xc940
	s_and_b32 s9, s8, 0xffc0
	s_and_b32 s8, s14, 0x7e0
	s_lshl_b32 s60, s8, 2
	s_add_u32 s60, s59, s60
	v_or_b32_e32 v5, s9, v6
	s_addc_u32 s61, s61, 0
	v_lshl_add_u64 v[20:21], s[60:61], 0, v[2:3]
	v_lshlrev_b32_e32 v22, 13, v5
	v_mov_b32_e32 v23, v3
	v_lshl_add_u64 v[20:21], v[20:21], 0, v[22:23]
	v_add_co_u32_e32 v22, vcc, s16, v20
	s_lshl_b32 s9, s9, 1
	s_nop 0
	v_addc_co_u32_e32 v23, vcc, 0, v21, vcc
	v_add_co_u32_e32 v24, vcc, s17, v20
	s_add_u32 s60, s56, s9
	s_nop 0
	v_addc_co_u32_e32 v25, vcc, 0, v21, vcc
	v_add_co_u32_e32 v26, vcc, s18, v20
	s_addc_u32 s61, s57, 0
	s_nop 0
	v_addc_co_u32_e32 v27, vcc, 0, v21, vcc
	v_add_co_u32_e32 v28, vcc, s19, v20
	v_readlane_b32 s69, v248, 19
	s_nop 0
	v_addc_co_u32_e32 v29, vcc, 0, v21, vcc
	v_add_co_u32_e32 v30, vcc, s20, v20
	v_readlane_b32 s70, v248, 20
	s_nop 0
	v_addc_co_u32_e32 v31, vcc, 0, v21, vcc
	v_add_co_u32_e32 v32, vcc, s21, v20
	v_readlane_b32 s71, v248, 21
	s_nop 0
	v_addc_co_u32_e32 v33, vcc, 0, v21, vcc
	v_add_co_u32_e32 v34, vcc, s22, v20
	v_readlane_b32 s72, v248, 22
	s_nop 0
	v_addc_co_u32_e32 v35, vcc, 0, v21, vcc
	global_load_dword v5, v[20:21], off nt
	global_load_dword v38, v[22:23], off nt
	global_load_dword v39, v[24:25], off nt
	global_load_dword v40, v[26:27], off nt
	global_load_dword v41, v[28:29], off nt
	global_load_dword v43, v[30:31], off nt
	global_load_dword v44, v[32:33], off nt
	global_load_dword v45, v[34:35], off nt
	v_add_co_u32_e32 v22, vcc, s23, v20
	v_readlane_b32 s73, v248, 23
	s_nop 0
	v_addc_co_u32_e32 v23, vcc, 0, v21, vcc
	v_add_co_u32_e32 v24, vcc, s24, v20
	v_readlane_b32 s74, v248, 24
	s_nop 0
	v_addc_co_u32_e32 v25, vcc, 0, v21, vcc
	v_add_co_u32_e32 v26, vcc, s25, v20
	v_readlane_b32 s75, v248, 25
	s_nop 0
	v_addc_co_u32_e32 v27, vcc, 0, v21, vcc
	v_add_co_u32_e32 v28, vcc, s26, v20
	v_readlane_b32 s76, v248, 26
	s_nop 0
	v_addc_co_u32_e32 v29, vcc, 0, v21, vcc
	v_add_co_u32_e32 v30, vcc, s27, v20
	v_readlane_b32 s77, v248, 27
	s_nop 0
	v_addc_co_u32_e32 v31, vcc, 0, v21, vcc
	v_add_co_u32_e32 v32, vcc, s28, v20
	v_readlane_b32 s80, v248, 30
	s_nop 0
	v_addc_co_u32_e32 v33, vcc, 0, v21, vcc
	v_add_co_u32_e32 v34, vcc, s29, v20
	v_readlane_b32 s81, v248, 31
	s_nop 0
	v_addc_co_u32_e32 v35, vcc, 0, v21, vcc
	v_add_co_u32_e32 v36, vcc, s30, v20
	v_readlane_b32 s82, v248, 32
	s_nop 0
	v_addc_co_u32_e32 v37, vcc, 0, v21, vcc
	global_load_dword v46, v[22:23], off nt
	global_load_dword v47, v[24:25], off nt
	global_load_dword v48, v[26:27], off nt
	global_load_dword v49, v[28:29], off nt
	global_load_dword v50, v[30:31], off nt
	global_load_dword v51, v[32:33], off nt
	global_load_dword v52, v[34:35], off nt
	global_load_dword v53, v[36:37], off nt
	v_add_co_u32_e32 v22, vcc, s31, v20
	v_readlane_b32 s83, v248, 33
	s_nop 0
	v_addc_co_u32_e32 v23, vcc, 0, v21, vcc
	v_add_co_u32_e32 v24, vcc, s36, v20
	s_nop 1
	v_addc_co_u32_e32 v25, vcc, 0, v21, vcc
	v_add_co_u32_e32 v26, vcc, s37, v20
	s_nop 1
	v_addc_co_u32_e32 v27, vcc, 0, v21, vcc
	v_add_co_u32_e32 v28, vcc, s38, v20
	s_nop 1
	v_addc_co_u32_e32 v29, vcc, 0, v21, vcc
	v_add_co_u32_e32 v30, vcc, s39, v20
	s_nop 1
	v_addc_co_u32_e32 v31, vcc, 0, v21, vcc
	v_add_co_u32_e32 v32, vcc, s40, v20
	s_nop 1
	v_addc_co_u32_e32 v33, vcc, 0, v21, vcc
	v_add_co_u32_e32 v34, vcc, s41, v20
	s_nop 1
	v_addc_co_u32_e32 v35, vcc, 0, v21, vcc
	v_add_co_u32_e32 v36, vcc, s42, v20
	s_nop 1
	v_addc_co_u32_e32 v37, vcc, 0, v21, vcc
	global_load_dword v54, v[22:23], off nt
	global_load_dword v55, v[24:25], off nt
	global_load_dword v56, v[26:27], off nt
	global_load_dword v57, v[28:29], off nt
	global_load_dword v58, v[30:31], off nt
	global_load_dword v59, v[32:33], off nt
	global_load_dword v60, v[34:35], off nt
	s_nop 0
	global_load_dword v36, v[36:37], off nt
	v_add_co_u32_e32 v22, vcc, s43, v20
	s_nop 1
	v_addc_co_u32_e32 v23, vcc, 0, v21, vcc
	v_add_co_u32_e32 v24, vcc, s44, v20
	s_nop 1
	v_addc_co_u32_e32 v25, vcc, 0, v21, vcc
	v_add_co_u32_e32 v26, vcc, s45, v20
	s_nop 1
	v_addc_co_u32_e32 v27, vcc, 0, v21, vcc
	v_add_co_u32_e32 v28, vcc, s46, v20
	s_nop 1
	v_addc_co_u32_e32 v29, vcc, 0, v21, vcc
	v_add_co_u32_e32 v30, vcc, s47, v20
	s_nop 1
	v_addc_co_u32_e32 v31, vcc, 0, v21, vcc
	v_add_co_u32_e32 v32, vcc, s48, v20
	s_nop 1
	v_addc_co_u32_e32 v33, vcc, 0, v21, vcc
	v_add_co_u32_e32 v34, vcc, s49, v20
	s_nop 1
	v_addc_co_u32_e32 v35, vcc, 0, v21, vcc
	v_add_co_u32_e32 v20, vcc, s50, v20
	s_nop 1
	v_addc_co_u32_e32 v21, vcc, 0, v21, vcc
	global_load_dword v22, v[22:23], off nt
	s_nop 0
	global_load_dword v23, v[24:25], off nt
	s_nop 0
	global_load_dword v24, v[26:27], off nt
	global_load_dword v25, v[28:29], off nt
	s_nop 0
	global_load_dword v26, v[30:31], off nt
	global_load_dword v27, v[32:33], off nt
	global_load_dword v28, v[34:35], off nt
	s_nop 0
	global_load_dword v20, v[20:21], off nt
	s_waitcnt vmcnt(30)
	ds_write2_b32 v7, v5, v38 offset1:66
	s_waitcnt vmcnt(28)
	ds_write2_b32 v7, v39, v40 offset0:132 offset1:198
	s_waitcnt vmcnt(26)
	ds_write2_b32 v13, v41, v43 offset0:8 offset1:74
	s_waitcnt vmcnt(24)
	ds_write2_b32 v13, v44, v45 offset0:140 offset1:206
	s_waitcnt vmcnt(22)
	ds_write2_b32 v14, v46, v47 offset0:16 offset1:82
	s_waitcnt vmcnt(20)
	ds_write2_b32 v14, v48, v49 offset0:148 offset1:214
	s_waitcnt vmcnt(18)
	ds_write2_b32 v15, v50, v51 offset0:24 offset1:90
	s_waitcnt vmcnt(16)
	ds_write2_b32 v15, v52, v53 offset0:156 offset1:222
	s_waitcnt vmcnt(14)
	ds_write2_b32 v16, v54, v55 offset0:32 offset1:98
	s_waitcnt vmcnt(12)
	ds_write2_b32 v16, v56, v57 offset0:164 offset1:230
	s_waitcnt vmcnt(10)
	ds_write2_b32 v17, v58, v59 offset0:40 offset1:106
	s_waitcnt vmcnt(8)
	ds_write2_b32 v17, v60, v36 offset0:172 offset1:238
	s_waitcnt vmcnt(6)
	ds_write2_b32 v18, v22, v23 offset0:48 offset1:114
	s_waitcnt vmcnt(4)
	ds_write2_b32 v18, v24, v25 offset0:180 offset1:246
	s_waitcnt vmcnt(2)
	ds_write2_b32 v19, v26, v27 offset0:56 offset1:122
	s_waitcnt vmcnt(0)
	ds_write2_b32 v19, v28, v20 offset0:188 offset1:254
	s_waitcnt lgkmcnt(0)
	ds_read2_b32 v[20:21], v9 offset1:33
	v_mov_b32_e32 v5, v3
	s_waitcnt lgkmcnt(0)
	v_cvt_pk_bf16_f32 v20, v20, v21
	ds_read2_b32 v[22:23], v9 offset0:66 offset1:99
	v_lshl_add_u64 v[26:27], s[60:61], 0, v[4:5]
	s_mov_b64 s[60:61], 0x3780000
	v_or_b32_e32 v5, s8, v8
	s_waitcnt lgkmcnt(0)
	v_cvt_pk_bf16_f32 v21, v22, v23
	ds_read2_b32 v[22:23], v9 offset0:132 offset1:165
	v_lshl_add_u64 v[26:27], v[26:27], 0, s[60:61]
	v_lshlrev_b32_e32 v28, 14, v5
	v_mov_b32_e32 v29, v3
	s_waitcnt lgkmcnt(0)
	v_cvt_pk_bf16_f32 v22, v22, v23
	ds_read2_b32 v[24:25], v9 offset0:198 offset1:231
	s_waitcnt lgkmcnt(0)
	v_cvt_pk_bf16_f32 v23, v24, v25
	v_lshl_add_u64 v[28:29], v[26:27], 0, v[28:29]
	ds_read2_b32 v[24:25], v9 offset0:8 offset1:41
	global_store_dwordx4 v[28:29], v[20:23], off
	v_or_b32_e32 v5, s8, v10
	v_lshlrev_b32_e32 v28, 14, v5
	s_waitcnt lgkmcnt(0)
	v_cvt_pk_bf16_f32 v20, v24, v25
	ds_read2_b32 v[22:23], v9 offset0:74 offset1:107
	s_waitcnt lgkmcnt(0)
	v_cvt_pk_bf16_f32 v21, v22, v23
	ds_read2_b32 v[22:23], v9 offset0:140 offset1:173
	v_mov_b32_e32 v29, v3
	s_waitcnt lgkmcnt(0)
	v_cvt_pk_bf16_f32 v22, v22, v23
	ds_read2_b32 v[24:25], v9 offset0:206 offset1:239
	s_waitcnt lgkmcnt(0)
	v_cvt_pk_bf16_f32 v23, v24, v25
	v_lshl_add_u64 v[28:29], v[26:27], 0, v[28:29]
	ds_read2_b32 v[24:25], v9 offset0:16 offset1:49
	global_store_dwordx4 v[28:29], v[20:23], off
	v_or_b32_e32 v5, s8, v11
	v_lshlrev_b32_e32 v28, 14, v5
	s_waitcnt lgkmcnt(0)
	v_cvt_pk_bf16_f32 v20, v24, v25
	ds_read2_b32 v[22:23], v9 offset0:82 offset1:115
	s_waitcnt lgkmcnt(0)
	v_cvt_pk_bf16_f32 v21, v22, v23
	ds_read2_b32 v[22:23], v9 offset0:148 offset1:181
	v_mov_b32_e32 v29, v3
	s_waitcnt lgkmcnt(0)
	v_cvt_pk_bf16_f32 v22, v22, v23
	ds_read2_b32 v[24:25], v9 offset0:214 offset1:247
	s_waitcnt lgkmcnt(0)
	v_cvt_pk_bf16_f32 v23, v24, v25
	v_lshl_add_u64 v[28:29], v[26:27], 0, v[28:29]
	ds_read2_b32 v[24:25], v9 offset0:24 offset1:57
	global_store_dwordx4 v[28:29], v[20:23], off
	v_or_b32_e32 v5, s8, v12
	s_mov_b64 s[8:9], 0
	s_waitcnt lgkmcnt(0)
	v_cvt_pk_bf16_f32 v20, v24, v25
	ds_read2_b32 v[22:23], v9 offset0:90 offset1:123
	s_waitcnt lgkmcnt(0)
	v_cvt_pk_bf16_f32 v21, v22, v23
	ds_read2_b32 v[22:23], v9 offset0:156 offset1:189
	s_waitcnt lgkmcnt(0)
	v_cvt_pk_bf16_f32 v22, v22, v23
	ds_read2_b32 v[24:25], v9 offset0:222 offset1:255
	s_waitcnt lgkmcnt(0)
	v_cvt_pk_bf16_f32 v23, v24, v25
	v_lshlrev_b32_e32 v24, 14, v5
	v_mov_b32_e32 v25, v3
	v_lshl_add_u64 v[24:25], v[26:27], 0, v[24:25]
	global_store_dwordx4 v[24:25], v[20:23], off
	s_waitcnt lgkmcnt(0)
.LBB0_28:
	s_andn2_b64 vcc, exec, s[8:9]
	s_cbranch_vccnz .LBB0_30
	v_readlane_b32 s68, v248, 18
	v_readlane_b32 s76, v248, 26
	v_readlane_b32 s77, v248, 27
	s_add_u32 s8, s76, s6
	s_addc_u32 s9, s77, s7
	s_add_i32 s6, s58, 0xe940
	s_bfe_u32 s7, s6, 0x80008
	s_lshl_b32 s6, s6, 5
	s_and_b32 s6, s6, 0x1fe0
	s_lshl_b32 s59, s6, 2
	s_add_u32 s8, s8, s59
	v_lshl_or_b32 v5, s7, 6, v6
	s_addc_u32 s9, s9, 0
	v_lshl_add_u64 v[20:21], s[8:9], 0, v[2:3]
	v_lshlrev_b32_e32 v22, 15, v5
	v_mov_b32_e32 v23, v3
	v_lshl_add_u64 v[20:21], v[20:21], 0, v[22:23]
	v_add_co_u32_e32 v22, vcc, s19, v20
	s_mov_b32 s8, 0x80000
	s_nop 0
	v_addc_co_u32_e32 v23, vcc, 0, v21, vcc
	v_add_co_u32_e32 v24, vcc, s23, v20
	s_lshl_b32 s7, s7, 7
	s_nop 0
	v_addc_co_u32_e32 v25, vcc, 0, v21, vcc
	v_add_co_u32_e32 v26, vcc, s27, v20
	v_readlane_b32 s69, v248, 19
	s_nop 0
	v_addc_co_u32_e32 v27, vcc, 0, v21, vcc
	v_add_co_u32_e32 v28, vcc, s31, v20
	v_readlane_b32 s70, v248, 20
	s_nop 0
	v_addc_co_u32_e32 v29, vcc, 0, v21, vcc
	v_add_co_u32_e32 v30, vcc, s39, v20
	v_readlane_b32 s71, v248, 21
	s_nop 0
	v_addc_co_u32_e32 v31, vcc, 0, v21, vcc
	v_add_co_u32_e32 v32, vcc, s43, v20
	v_readlane_b32 s72, v248, 22
	s_nop 0
	v_addc_co_u32_e32 v33, vcc, 0, v21, vcc
	v_add_co_u32_e32 v34, vcc, s47, v20
	v_readlane_b32 s73, v248, 23
	s_nop 0
	v_addc_co_u32_e32 v35, vcc, 0, v21, vcc
	global_load_dword v5, v[20:21], off nt
	global_load_dword v38, v[22:23], off nt
	global_load_dword v39, v[24:25], off nt
	global_load_dword v40, v[26:27], off nt
	global_load_dword v41, v[28:29], off nt
	global_load_dword v43, v[30:31], off nt
	global_load_dword v44, v[32:33], off nt
	global_load_dword v45, v[34:35], off nt
	v_add_co_u32_e32 v22, vcc, s8, v20
	s_mov_b32 s8, 0x90000
	s_nop 0
	v_addc_co_u32_e32 v23, vcc, 0, v21, vcc
	v_add_co_u32_e32 v24, vcc, s8, v20
	s_mov_b32 s8, 0xa0000
	s_nop 0
	v_addc_co_u32_e32 v25, vcc, 0, v21, vcc
	v_add_co_u32_e32 v26, vcc, s8, v20
	s_mov_b32 s8, 0xb0000
	s_nop 0
	v_addc_co_u32_e32 v27, vcc, 0, v21, vcc
	v_add_co_u32_e32 v28, vcc, s8, v20
	s_mov_b32 s8, 0xc0000
	s_nop 0
	v_addc_co_u32_e32 v29, vcc, 0, v21, vcc
	v_add_co_u32_e32 v30, vcc, s8, v20
	s_mov_b32 s8, 0xd0000
	s_nop 0
	v_addc_co_u32_e32 v31, vcc, 0, v21, vcc
	v_add_co_u32_e32 v32, vcc, s8, v20
	s_mov_b32 s8, 0xe0000
	s_nop 0
	v_addc_co_u32_e32 v33, vcc, 0, v21, vcc
	v_add_co_u32_e32 v34, vcc, s8, v20
	s_mov_b32 s8, 0xf0000
	s_nop 0
	v_addc_co_u32_e32 v35, vcc, 0, v21, vcc
	v_add_co_u32_e32 v36, vcc, s8, v20
	s_mov_b32 s8, 0x100000
	s_nop 0
	v_addc_co_u32_e32 v37, vcc, 0, v21, vcc
	global_load_dword v46, v[22:23], off nt
	global_load_dword v47, v[24:25], off nt
	global_load_dword v48, v[26:27], off nt
	global_load_dword v49, v[28:29], off nt
	global_load_dword v50, v[30:31], off nt
	global_load_dword v51, v[32:33], off nt
	global_load_dword v52, v[34:35], off nt
	global_load_dword v53, v[36:37], off nt
	v_add_co_u32_e32 v22, vcc, s8, v20
	s_mov_b32 s8, 0x110000
	s_nop 0
	v_addc_co_u32_e32 v23, vcc, 0, v21, vcc
	v_add_co_u32_e32 v24, vcc, s8, v20
	s_mov_b32 s8, 0x120000
	s_nop 0
	v_addc_co_u32_e32 v25, vcc, 0, v21, vcc
	v_add_co_u32_e32 v26, vcc, s8, v20
	s_mov_b32 s8, 0x130000
	s_nop 0
	v_addc_co_u32_e32 v27, vcc, 0, v21, vcc
	v_add_co_u32_e32 v28, vcc, s8, v20
	s_mov_b32 s8, 0x140000
	s_nop 0
	v_addc_co_u32_e32 v29, vcc, 0, v21, vcc
	v_add_co_u32_e32 v30, vcc, s8, v20
	s_mov_b32 s8, 0x150000
	s_nop 0
	v_addc_co_u32_e32 v31, vcc, 0, v21, vcc
	v_add_co_u32_e32 v32, vcc, s8, v20
	s_mov_b32 s8, 0x160000
	s_nop 0
	v_addc_co_u32_e32 v33, vcc, 0, v21, vcc
	v_add_co_u32_e32 v34, vcc, s8, v20
	s_mov_b32 s8, 0x170000
	s_nop 0
	v_addc_co_u32_e32 v35, vcc, 0, v21, vcc
	v_add_co_u32_e32 v36, vcc, s8, v20
	s_mov_b32 s8, 0x180000
	s_nop 0
	v_addc_co_u32_e32 v37, vcc, 0, v21, vcc
	global_load_dword v54, v[22:23], off nt
	global_load_dword v55, v[24:25], off nt
	global_load_dword v56, v[26:27], off nt
	global_load_dword v57, v[28:29], off nt
	global_load_dword v58, v[30:31], off nt
	global_load_dword v59, v[32:33], off nt
	global_load_dword v60, v[34:35], off nt
	s_nop 0
	global_load_dword v36, v[36:37], off nt
	v_add_co_u32_e32 v22, vcc, s8, v20
	s_mov_b32 s8, 0x190000
	s_nop 0
	v_addc_co_u32_e32 v23, vcc, 0, v21, vcc
	v_add_co_u32_e32 v24, vcc, s8, v20
	s_mov_b32 s8, 0x1a0000
	s_nop 0
	v_addc_co_u32_e32 v25, vcc, 0, v21, vcc
	v_add_co_u32_e32 v26, vcc, s8, v20
	s_mov_b32 s8, 0x1b0000
	s_nop 0
	v_addc_co_u32_e32 v27, vcc, 0, v21, vcc
	v_add_co_u32_e32 v28, vcc, s8, v20
	s_mov_b32 s8, 0x1c0000
	s_nop 0
	v_addc_co_u32_e32 v29, vcc, 0, v21, vcc
	v_add_co_u32_e32 v30, vcc, s8, v20
	s_mov_b32 s8, 0x1d0000
	s_nop 0
	v_addc_co_u32_e32 v31, vcc, 0, v21, vcc
	v_add_co_u32_e32 v32, vcc, s8, v20
	s_mov_b32 s8, 0x1e0000
	s_nop 0
	v_addc_co_u32_e32 v33, vcc, 0, v21, vcc
	v_add_co_u32_e32 v34, vcc, s8, v20
	s_mov_b32 s8, 0x1f0000
	s_nop 0
	v_addc_co_u32_e32 v35, vcc, 0, v21, vcc
	v_add_co_u32_e32 v20, vcc, s8, v20
	s_add_u32 s8, s56, s7
	s_nop 0
	v_addc_co_u32_e32 v21, vcc, 0, v21, vcc
	global_load_dword v22, v[22:23], off nt
	s_nop 0
	global_load_dword v23, v[24:25], off nt
	s_nop 0
	global_load_dword v24, v[26:27], off nt
	global_load_dword v25, v[28:29], off nt
	s_nop 0
	global_load_dword v26, v[30:31], off nt
	global_load_dword v27, v[32:33], off nt
	global_load_dword v28, v[34:35], off nt
	s_nop 0
	global_load_dword v20, v[20:21], off nt
	s_waitcnt vmcnt(30)
	ds_write2_b32 v7, v5, v38 offset1:66
	s_waitcnt vmcnt(28)
	ds_write2_b32 v7, v39, v40 offset0:132 offset1:198
	s_waitcnt vmcnt(26)
	ds_write2_b32 v13, v41, v43 offset0:8 offset1:74
	s_waitcnt vmcnt(24)
	ds_write2_b32 v13, v44, v45 offset0:140 offset1:206
	s_waitcnt vmcnt(22)
	ds_write2_b32 v14, v46, v47 offset0:16 offset1:82
	s_waitcnt vmcnt(20)
	ds_write2_b32 v14, v48, v49 offset0:148 offset1:214
	s_waitcnt vmcnt(18)
	ds_write2_b32 v15, v50, v51 offset0:24 offset1:90
	s_waitcnt vmcnt(16)
	ds_write2_b32 v15, v52, v53 offset0:156 offset1:222
	s_waitcnt vmcnt(14)
	ds_write2_b32 v16, v54, v55 offset0:32 offset1:98
	s_waitcnt vmcnt(12)
	ds_write2_b32 v16, v56, v57 offset0:164 offset1:230
	s_waitcnt vmcnt(10)
	ds_write2_b32 v17, v58, v59 offset0:40 offset1:106
	s_waitcnt vmcnt(8)
	ds_write2_b32 v17, v60, v36 offset0:172 offset1:238
	s_waitcnt vmcnt(6)
	ds_write2_b32 v18, v22, v23 offset0:48 offset1:114
	s_waitcnt vmcnt(4)
	ds_write2_b32 v18, v24, v25 offset0:180 offset1:246
	s_waitcnt vmcnt(2)
	ds_write2_b32 v19, v26, v27 offset0:56 offset1:122
	s_waitcnt vmcnt(0)
	ds_write2_b32 v19, v28, v20 offset0:188 offset1:254
	s_waitcnt lgkmcnt(0)
	ds_read2_b32 v[20:21], v9 offset1:33
	s_addc_u32 s9, s57, 0
	v_mov_b32_e32 v5, v3
	s_waitcnt lgkmcnt(0)
	v_cvt_pk_bf16_f32 v20, v20, v21
	ds_read2_b32 v[22:23], v9 offset0:66 offset1:99
	v_lshl_add_u64 v[26:27], s[8:9], 0, v[4:5]
	s_mov_b64 s[8:9], 0x1780000
	v_or_b32_e32 v5, s6, v8
	s_waitcnt lgkmcnt(0)
	v_cvt_pk_bf16_f32 v21, v22, v23
	ds_read2_b32 v[22:23], v9 offset0:132 offset1:165
	v_lshl_add_u64 v[26:27], v[26:27], 0, s[8:9]
	v_lshlrev_b32_e32 v28, 12, v5
	v_mov_b32_e32 v29, v3
	s_waitcnt lgkmcnt(0)
	v_cvt_pk_bf16_f32 v22, v22, v23
	ds_read2_b32 v[24:25], v9 offset0:198 offset1:231
	s_waitcnt lgkmcnt(0)
	v_cvt_pk_bf16_f32 v23, v24, v25
	v_lshl_add_u64 v[28:29], v[26:27], 0, v[28:29]
	ds_read2_b32 v[24:25], v9 offset0:8 offset1:41
	global_store_dwordx4 v[28:29], v[20:23], off
	v_or_b32_e32 v5, s6, v10
	v_lshlrev_b32_e32 v28, 12, v5
	s_waitcnt lgkmcnt(0)
	v_cvt_pk_bf16_f32 v20, v24, v25
	ds_read2_b32 v[22:23], v9 offset0:74 offset1:107
	s_waitcnt lgkmcnt(0)
	v_cvt_pk_bf16_f32 v21, v22, v23
	ds_read2_b32 v[22:23], v9 offset0:140 offset1:173
	v_mov_b32_e32 v29, v3
	s_waitcnt lgkmcnt(0)
	v_cvt_pk_bf16_f32 v22, v22, v23
	ds_read2_b32 v[24:25], v9 offset0:206 offset1:239
	s_waitcnt lgkmcnt(0)
	v_cvt_pk_bf16_f32 v23, v24, v25
	v_lshl_add_u64 v[28:29], v[26:27], 0, v[28:29]
	ds_read2_b32 v[24:25], v9 offset0:16 offset1:49
	global_store_dwordx4 v[28:29], v[20:23], off
	v_or_b32_e32 v5, s6, v11
	v_lshlrev_b32_e32 v28, 12, v5
	s_waitcnt lgkmcnt(0)
	v_cvt_pk_bf16_f32 v20, v24, v25
	ds_read2_b32 v[22:23], v9 offset0:82 offset1:115
	s_waitcnt lgkmcnt(0)
	v_cvt_pk_bf16_f32 v21, v22, v23
	ds_read2_b32 v[22:23], v9 offset0:148 offset1:181
	v_mov_b32_e32 v29, v3
	s_waitcnt lgkmcnt(0)
	v_cvt_pk_bf16_f32 v22, v22, v23
	ds_read2_b32 v[24:25], v9 offset0:214 offset1:247
	s_waitcnt lgkmcnt(0)
	v_cvt_pk_bf16_f32 v23, v24, v25
	v_lshl_add_u64 v[28:29], v[26:27], 0, v[28:29]
	ds_read2_b32 v[24:25], v9 offset0:24 offset1:57
	global_store_dwordx4 v[28:29], v[20:23], off
	v_or_b32_e32 v5, s6, v12
	v_readlane_b32 s74, v248, 24
	s_waitcnt lgkmcnt(0)
	v_cvt_pk_bf16_f32 v20, v24, v25
	ds_read2_b32 v[22:23], v9 offset0:90 offset1:123
	s_waitcnt lgkmcnt(0)
	v_cvt_pk_bf16_f32 v21, v22, v23
	ds_read2_b32 v[22:23], v9 offset0:156 offset1:189
	s_waitcnt lgkmcnt(0)
	v_cvt_pk_bf16_f32 v22, v22, v23
	ds_read2_b32 v[24:25], v9 offset0:222 offset1:255
	s_waitcnt lgkmcnt(0)
	v_cvt_pk_bf16_f32 v23, v24, v25
	v_lshlrev_b32_e32 v24, 12, v5
	v_mov_b32_e32 v25, v3
	v_lshl_add_u64 v[24:25], v[26:27], 0, v[24:25]
	global_store_dwordx4 v[24:25], v[20:23], off
	s_waitcnt lgkmcnt(0)
	v_readlane_b32 s75, v248, 25
	v_readlane_b32 s78, v248, 28
	v_readlane_b32 s79, v248, 29
	v_readlane_b32 s80, v248, 30
	v_readlane_b32 s81, v248, 31
	v_readlane_b32 s82, v248, 32
	v_readlane_b32 s83, v248, 33

.LBB0_31:
	s_andn2_b64 vcc, exec, s[6:7]
	s_cbranch_vccnz .LBB0_33
	v_readlane_b32 s68, v248, 18
	s_lshl_b64 s[6:7], s[0:1], 24
	v_readlane_b32 s74, v248, 24
	v_readlane_b32 s75, v248, 25
	s_add_u32 s8, s74, s6
	s_addc_u32 s9, s75, s7
	s_add_i32 s6, s58, 0xf140
	s_and_b32 s7, s6, 0xffc0
	s_and_b32 s6, s14, 0x7e0
	s_lshl_b32 s59, s6, 2
	s_add_u32 s8, s8, s59
	v_or_b32_e32 v5, s7, v6
	s_addc_u32 s9, s9, 0
	v_lshl_add_u64 v[20:21], s[8:9], 0, v[2:3]
	v_lshlrev_b32_e32 v22, 13, v5
	v_mov_b32_e32 v23, v3
	v_lshl_add_u64 v[20:21], v[20:21], 0, v[22:23]
	v_add_co_u32_e32 v22, vcc, s16, v20
	s_lshl_b32 s7, s7, 1
	s_nop 0
	v_addc_co_u32_e32 v23, vcc, 0, v21, vcc
	v_add_co_u32_e32 v24, vcc, s17, v20
	s_add_u32 s8, s56, s7
	s_nop 0
	v_addc_co_u32_e32 v25, vcc, 0, v21, vcc
	v_add_co_u32_e32 v26, vcc, s18, v20
	s_addc_u32 s9, s57, 0
	s_nop 0
	v_addc_co_u32_e32 v27, vcc, 0, v21, vcc
	v_add_co_u32_e32 v28, vcc, s19, v20
	v_readlane_b32 s69, v248, 19
	s_nop 0
	v_addc_co_u32_e32 v29, vcc, 0, v21, vcc
	v_add_co_u32_e32 v30, vcc, s20, v20
	v_readlane_b32 s70, v248, 20
	s_nop 0
	v_addc_co_u32_e32 v31, vcc, 0, v21, vcc
	v_add_co_u32_e32 v32, vcc, s21, v20
	v_readlane_b32 s71, v248, 21
	s_nop 0
	v_addc_co_u32_e32 v33, vcc, 0, v21, vcc
	v_add_co_u32_e32 v34, vcc, s22, v20
	v_readlane_b32 s72, v248, 22
	s_nop 0
	v_addc_co_u32_e32 v35, vcc, 0, v21, vcc
	global_load_dword v5, v[20:21], off nt
	global_load_dword v38, v[22:23], off nt
	global_load_dword v39, v[24:25], off nt
	global_load_dword v40, v[26:27], off nt
	global_load_dword v41, v[28:29], off nt
	global_load_dword v43, v[30:31], off nt
	global_load_dword v44, v[32:33], off nt
	global_load_dword v45, v[34:35], off nt
	v_add_co_u32_e32 v22, vcc, s23, v20
	v_readlane_b32 s73, v248, 23
	s_nop 0
	v_addc_co_u32_e32 v23, vcc, 0, v21, vcc
	v_add_co_u32_e32 v24, vcc, s24, v20
	v_readlane_b32 s76, v248, 26
	s_nop 0
	v_addc_co_u32_e32 v25, vcc, 0, v21, vcc
	v_add_co_u32_e32 v26, vcc, s25, v20
	v_readlane_b32 s77, v248, 27
	s_nop 0
	v_addc_co_u32_e32 v27, vcc, 0, v21, vcc
	v_add_co_u32_e32 v28, vcc, s26, v20
	v_readlane_b32 s78, v248, 28
	s_nop 0
	v_addc_co_u32_e32 v29, vcc, 0, v21, vcc
	v_add_co_u32_e32 v30, vcc, s27, v20
	v_readlane_b32 s79, v248, 29
	s_nop 0
	v_addc_co_u32_e32 v31, vcc, 0, v21, vcc
	v_add_co_u32_e32 v32, vcc, s28, v20
	v_readlane_b32 s80, v248, 30
	s_nop 0
	v_addc_co_u32_e32 v33, vcc, 0, v21, vcc
	v_add_co_u32_e32 v34, vcc, s29, v20
	v_readlane_b32 s81, v248, 31
	s_nop 0
	v_addc_co_u32_e32 v35, vcc, 0, v21, vcc
	v_add_co_u32_e32 v36, vcc, s30, v20
	v_readlane_b32 s82, v248, 32
	s_nop 0
	v_addc_co_u32_e32 v37, vcc, 0, v21, vcc
	global_load_dword v46, v[22:23], off nt
	global_load_dword v47, v[24:25], off nt
	global_load_dword v48, v[26:27], off nt
	global_load_dword v49, v[28:29], off nt
	global_load_dword v50, v[30:31], off nt
	global_load_dword v51, v[32:33], off nt
	global_load_dword v52, v[34:35], off nt
	global_load_dword v53, v[36:37], off nt
	v_add_co_u32_e32 v22, vcc, s31, v20
	v_readlane_b32 s83, v248, 33
	s_nop 0
	v_addc_co_u32_e32 v23, vcc, 0, v21, vcc
	v_add_co_u32_e32 v24, vcc, s36, v20
	s_nop 1
	v_addc_co_u32_e32 v25, vcc, 0, v21, vcc
	v_add_co_u32_e32 v26, vcc, s37, v20
	s_nop 1
	v_addc_co_u32_e32 v27, vcc, 0, v21, vcc
	v_add_co_u32_e32 v28, vcc, s38, v20
	s_nop 1
	v_addc_co_u32_e32 v29, vcc, 0, v21, vcc
	v_add_co_u32_e32 v30, vcc, s39, v20
	s_nop 1
	v_addc_co_u32_e32 v31, vcc, 0, v21, vcc
	v_add_co_u32_e32 v32, vcc, s40, v20
	s_nop 1
	v_addc_co_u32_e32 v33, vcc, 0, v21, vcc
	v_add_co_u32_e32 v34, vcc, s41, v20
	s_nop 1
	v_addc_co_u32_e32 v35, vcc, 0, v21, vcc
	v_add_co_u32_e32 v36, vcc, s42, v20
	s_nop 1
	v_addc_co_u32_e32 v37, vcc, 0, v21, vcc
	global_load_dword v54, v[22:23], off nt
	global_load_dword v55, v[24:25], off nt
	global_load_dword v56, v[26:27], off nt
	global_load_dword v57, v[28:29], off nt
	global_load_dword v58, v[30:31], off nt
	global_load_dword v59, v[32:33], off nt
	global_load_dword v60, v[34:35], off nt
	s_nop 0
	global_load_dword v36, v[36:37], off nt
	v_add_co_u32_e32 v22, vcc, s43, v20
	s_nop 1
	v_addc_co_u32_e32 v23, vcc, 0, v21, vcc
	v_add_co_u32_e32 v24, vcc, s44, v20
	s_nop 1
	v_addc_co_u32_e32 v25, vcc, 0, v21, vcc
	v_add_co_u32_e32 v26, vcc, s45, v20
	s_nop 1
	v_addc_co_u32_e32 v27, vcc, 0, v21, vcc
	v_add_co_u32_e32 v28, vcc, s46, v20
	s_nop 1
	v_addc_co_u32_e32 v29, vcc, 0, v21, vcc
	v_add_co_u32_e32 v30, vcc, s47, v20
	s_nop 1
	v_addc_co_u32_e32 v31, vcc, 0, v21, vcc
	v_add_co_u32_e32 v32, vcc, s48, v20
	s_nop 1
	v_addc_co_u32_e32 v33, vcc, 0, v21, vcc
	v_add_co_u32_e32 v34, vcc, s49, v20
	s_nop 1
	v_addc_co_u32_e32 v35, vcc, 0, v21, vcc
	v_add_co_u32_e32 v20, vcc, s50, v20
	s_nop 1
	v_addc_co_u32_e32 v21, vcc, 0, v21, vcc
	global_load_dword v22, v[22:23], off nt
	s_nop 0
	global_load_dword v23, v[24:25], off nt
	s_nop 0
	global_load_dword v24, v[26:27], off nt
	global_load_dword v25, v[28:29], off nt
	s_nop 0
	global_load_dword v26, v[30:31], off nt
	global_load_dword v27, v[32:33], off nt
	global_load_dword v28, v[34:35], off nt
	s_nop 0
	global_load_dword v20, v[20:21], off nt
	s_waitcnt vmcnt(30)
	ds_write2_b32 v7, v5, v38 offset1:66
	s_waitcnt vmcnt(28)
	ds_write2_b32 v7, v39, v40 offset0:132 offset1:198
	s_waitcnt vmcnt(26)
	ds_write2_b32 v13, v41, v43 offset0:8 offset1:74
	s_waitcnt vmcnt(24)
	ds_write2_b32 v13, v44, v45 offset0:140 offset1:206
	s_waitcnt vmcnt(22)
	ds_write2_b32 v14, v46, v47 offset0:16 offset1:82
	s_waitcnt vmcnt(20)
	ds_write2_b32 v14, v48, v49 offset0:148 offset1:214
	s_waitcnt vmcnt(18)
	ds_write2_b32 v15, v50, v51 offset0:24 offset1:90
	s_waitcnt vmcnt(16)
	ds_write2_b32 v15, v52, v53 offset0:156 offset1:222
	s_waitcnt vmcnt(14)
	ds_write2_b32 v16, v54, v55 offset0:32 offset1:98
	s_waitcnt vmcnt(12)
	ds_write2_b32 v16, v56, v57 offset0:164 offset1:230
	s_waitcnt vmcnt(10)
	ds_write2_b32 v17, v58, v59 offset0:40 offset1:106
	s_waitcnt vmcnt(8)
	ds_write2_b32 v17, v60, v36 offset0:172 offset1:238
	s_waitcnt vmcnt(6)
	ds_write2_b32 v18, v22, v23 offset0:48 offset1:114
	s_waitcnt vmcnt(4)
	ds_write2_b32 v18, v24, v25 offset0:180 offset1:246
	s_waitcnt vmcnt(2)
	ds_write2_b32 v19, v26, v27 offset0:56 offset1:122
	s_waitcnt vmcnt(0)
	ds_write2_b32 v19, v28, v20 offset0:188 offset1:254
	s_waitcnt lgkmcnt(0)
	ds_read2_b32 v[20:21], v9 offset1:33
	v_mov_b32_e32 v5, v3
	s_waitcnt lgkmcnt(0)
	v_cvt_pk_bf16_f32 v20, v20, v21
	ds_read2_b32 v[22:23], v9 offset0:66 offset1:99
	v_lshl_add_u64 v[26:27], s[8:9], 0, v[4:5]
	s_mov_b64 s[8:9], 0xf80000
	v_or_b32_e32 v5, s6, v8
	s_waitcnt lgkmcnt(0)
	v_cvt_pk_bf16_f32 v21, v22, v23
	ds_read2_b32 v[22:23], v9 offset0:132 offset1:165
	v_lshl_add_u64 v[26:27], v[26:27], 0, s[8:9]
	v_lshlrev_b32_e32 v28, 12, v5
	v_mov_b32_e32 v29, v3
	s_waitcnt lgkmcnt(0)
	v_cvt_pk_bf16_f32 v22, v22, v23
	ds_read2_b32 v[24:25], v9 offset0:198 offset1:231
	s_waitcnt lgkmcnt(0)
	v_cvt_pk_bf16_f32 v23, v24, v25
	v_lshl_add_u64 v[28:29], v[26:27], 0, v[28:29]
	ds_read2_b32 v[24:25], v9 offset0:8 offset1:41
	global_store_dwordx4 v[28:29], v[20:23], off
	v_or_b32_e32 v5, s6, v10
	v_lshlrev_b32_e32 v28, 12, v5
	s_waitcnt lgkmcnt(0)
	v_cvt_pk_bf16_f32 v20, v24, v25
	ds_read2_b32 v[22:23], v9 offset0:74 offset1:107
	s_waitcnt lgkmcnt(0)
	v_cvt_pk_bf16_f32 v21, v22, v23
	ds_read2_b32 v[22:23], v9 offset0:140 offset1:173
	v_mov_b32_e32 v29, v3
	s_waitcnt lgkmcnt(0)
	v_cvt_pk_bf16_f32 v22, v22, v23
	ds_read2_b32 v[24:25], v9 offset0:206 offset1:239
	s_waitcnt lgkmcnt(0)
	v_cvt_pk_bf16_f32 v23, v24, v25
	v_lshl_add_u64 v[28:29], v[26:27], 0, v[28:29]
	ds_read2_b32 v[24:25], v9 offset0:16 offset1:49
	global_store_dwordx4 v[28:29], v[20:23], off
	v_or_b32_e32 v5, s6, v11
	v_lshlrev_b32_e32 v28, 12, v5
	s_waitcnt lgkmcnt(0)
	v_cvt_pk_bf16_f32 v20, v24, v25
	ds_read2_b32 v[22:23], v9 offset0:82 offset1:115
	s_waitcnt lgkmcnt(0)
	v_cvt_pk_bf16_f32 v21, v22, v23
	ds_read2_b32 v[22:23], v9 offset0:148 offset1:181
	v_mov_b32_e32 v29, v3
	s_waitcnt lgkmcnt(0)
	v_cvt_pk_bf16_f32 v22, v22, v23
	ds_read2_b32 v[24:25], v9 offset0:214 offset1:247
	s_waitcnt lgkmcnt(0)
	v_cvt_pk_bf16_f32 v23, v24, v25
	v_lshl_add_u64 v[28:29], v[26:27], 0, v[28:29]
	ds_read2_b32 v[24:25], v9 offset0:24 offset1:57
	global_store_dwordx4 v[28:29], v[20:23], off
	v_or_b32_e32 v5, s6, v12
	s_waitcnt lgkmcnt(0)
	v_cvt_pk_bf16_f32 v20, v24, v25
	ds_read2_b32 v[22:23], v9 offset0:90 offset1:123
	s_waitcnt lgkmcnt(0)
	v_cvt_pk_bf16_f32 v21, v22, v23
	ds_read2_b32 v[22:23], v9 offset0:156 offset1:189
	s_waitcnt lgkmcnt(0)
	v_cvt_pk_bf16_f32 v22, v22, v23
	ds_read2_b32 v[24:25], v9 offset0:222 offset1:255
	s_waitcnt lgkmcnt(0)
	v_cvt_pk_bf16_f32 v23, v24, v25
	v_lshlrev_b32_e32 v24, 12, v5
	v_mov_b32_e32 v25, v3
	v_lshl_add_u64 v[24:25], v[26:27], 0, v[24:25]
	global_store_dwordx4 v[24:25], v[20:23], off
	s_waitcnt lgkmcnt(0)

.LBB0_34:
	s_andn2_b64 vcc, exec, s[6:7]
	s_cbranch_vccnz .LBB0_36
	v_readlane_b32 s68, v248, 2
	s_lshl_b64 s[6:7], s[0:1], 22
	v_readlane_b32 s76, v248, 10
	v_readlane_b32 s77, v248, 11
	s_add_u32 s8, s76, s6
	s_addc_u32 s7, s77, s7
	s_add_i32 s1, s58, 0xf340
	s_and_b32 s6, s1, 0xffc0
	s_and_b32 s1, s14, 0x7e0
	s_lshl_b32 s9, s1, 2
	s_add_u32 s8, s8, s9
	v_or_b32_e32 v5, s6, v6
	s_addc_u32 s9, s7, 0
	v_lshl_add_u64 v[20:21], s[8:9], 0, v[2:3]
	v_lshlrev_b32_e32 v22, 13, v5
	v_mov_b32_e32 v23, v3
	v_lshl_add_u64 v[20:21], v[20:21], 0, v[22:23]
	v_add_co_u32_e32 v22, vcc, s16, v20
	s_lshl_b32 s6, s6, 1
	s_nop 0
	v_addc_co_u32_e32 v23, vcc, 0, v21, vcc
	v_add_co_u32_e32 v24, vcc, s17, v20
	s_add_u32 s6, s56, s6
	s_nop 0
	v_addc_co_u32_e32 v25, vcc, 0, v21, vcc
	v_add_co_u32_e32 v26, vcc, s18, v20
	s_addc_u32 s7, s57, 0
	s_nop 0
	v_addc_co_u32_e32 v27, vcc, 0, v21, vcc
	v_add_co_u32_e32 v28, vcc, s19, v20
	v_readlane_b32 s69, v248, 3
	s_nop 0
	v_addc_co_u32_e32 v29, vcc, 0, v21, vcc
	v_add_co_u32_e32 v30, vcc, s20, v20
	v_readlane_b32 s70, v248, 4
	s_nop 0
	v_addc_co_u32_e32 v31, vcc, 0, v21, vcc
	v_add_co_u32_e32 v32, vcc, s21, v20
	v_readlane_b32 s71, v248, 5
	s_nop 0
	v_addc_co_u32_e32 v33, vcc, 0, v21, vcc
	v_add_co_u32_e32 v34, vcc, s22, v20
	v_readlane_b32 s72, v248, 6
	s_nop 0
	v_addc_co_u32_e32 v35, vcc, 0, v21, vcc
	global_load_dword v5, v[20:21], off nt
	global_load_dword v38, v[22:23], off nt
	global_load_dword v39, v[24:25], off nt
	global_load_dword v40, v[26:27], off nt
	global_load_dword v41, v[28:29], off nt
	global_load_dword v43, v[30:31], off nt
	global_load_dword v44, v[32:33], off nt
	global_load_dword v45, v[34:35], off nt
	v_add_co_u32_e32 v22, vcc, s23, v20
	v_readlane_b32 s73, v248, 7
	s_nop 0
	v_addc_co_u32_e32 v23, vcc, 0, v21, vcc
	v_add_co_u32_e32 v24, vcc, s24, v20
	v_readlane_b32 s74, v248, 8
	s_nop 0
	v_addc_co_u32_e32 v25, vcc, 0, v21, vcc
	v_add_co_u32_e32 v26, vcc, s25, v20
	v_readlane_b32 s75, v248, 9
	s_nop 0
	v_addc_co_u32_e32 v27, vcc, 0, v21, vcc
	v_add_co_u32_e32 v28, vcc, s26, v20
	v_readlane_b32 s78, v248, 12
	s_nop 0
	v_addc_co_u32_e32 v29, vcc, 0, v21, vcc
	v_add_co_u32_e32 v30, vcc, s27, v20
	v_readlane_b32 s79, v248, 13
	s_nop 0
	v_addc_co_u32_e32 v31, vcc, 0, v21, vcc
	v_add_co_u32_e32 v32, vcc, s28, v20
	v_readlane_b32 s80, v248, 14
	s_nop 0
	v_addc_co_u32_e32 v33, vcc, 0, v21, vcc
	v_add_co_u32_e32 v34, vcc, s29, v20
	v_readlane_b32 s81, v248, 15
	s_nop 0
	v_addc_co_u32_e32 v35, vcc, 0, v21, vcc
	v_add_co_u32_e32 v36, vcc, s30, v20
	v_readlane_b32 s82, v248, 16
	s_nop 0
	v_addc_co_u32_e32 v37, vcc, 0, v21, vcc
	global_load_dword v46, v[22:23], off nt
	global_load_dword v47, v[24:25], off nt
	global_load_dword v48, v[26:27], off nt
	global_load_dword v49, v[28:29], off nt
	global_load_dword v50, v[30:31], off nt
	global_load_dword v51, v[32:33], off nt
	global_load_dword v52, v[34:35], off nt
	global_load_dword v53, v[36:37], off nt
	v_add_co_u32_e32 v22, vcc, s31, v20
	v_readlane_b32 s83, v248, 17
	s_nop 0
	v_addc_co_u32_e32 v23, vcc, 0, v21, vcc
	v_add_co_u32_e32 v24, vcc, s36, v20
	s_nop 1
	v_addc_co_u32_e32 v25, vcc, 0, v21, vcc
	v_add_co_u32_e32 v26, vcc, s37, v20
	s_nop 1
	v_addc_co_u32_e32 v27, vcc, 0, v21, vcc
	v_add_co_u32_e32 v28, vcc, s38, v20
	s_nop 1
	v_addc_co_u32_e32 v29, vcc, 0, v21, vcc
	v_add_co_u32_e32 v30, vcc, s39, v20
	s_nop 1
	v_addc_co_u32_e32 v31, vcc, 0, v21, vcc
	v_add_co_u32_e32 v32, vcc, s40, v20
	s_nop 1
	v_addc_co_u32_e32 v33, vcc, 0, v21, vcc
	v_add_co_u32_e32 v34, vcc, s41, v20
	s_nop 1
	v_addc_co_u32_e32 v35, vcc, 0, v21, vcc
	v_add_co_u32_e32 v36, vcc, s42, v20
	s_nop 1
	v_addc_co_u32_e32 v37, vcc, 0, v21, vcc
	global_load_dword v54, v[22:23], off nt
	global_load_dword v55, v[24:25], off nt
	global_load_dword v56, v[26:27], off nt
	global_load_dword v57, v[28:29], off nt
	global_load_dword v58, v[30:31], off nt
	global_load_dword v59, v[32:33], off nt
	global_load_dword v60, v[34:35], off nt
	s_nop 0
	global_load_dword v36, v[36:37], off nt
	v_add_co_u32_e32 v22, vcc, s43, v20
	s_nop 1
	v_addc_co_u32_e32 v23, vcc, 0, v21, vcc
	v_add_co_u32_e32 v24, vcc, s44, v20
	s_nop 1
	v_addc_co_u32_e32 v25, vcc, 0, v21, vcc
	v_add_co_u32_e32 v26, vcc, s45, v20
	s_nop 1
	v_addc_co_u32_e32 v27, vcc, 0, v21, vcc
	v_add_co_u32_e32 v28, vcc, s46, v20
	s_nop 1
	v_addc_co_u32_e32 v29, vcc, 0, v21, vcc
	v_add_co_u32_e32 v30, vcc, s47, v20
	s_nop 1
	v_addc_co_u32_e32 v31, vcc, 0, v21, vcc
	v_add_co_u32_e32 v32, vcc, s48, v20
	s_nop 1
	v_addc_co_u32_e32 v33, vcc, 0, v21, vcc
	v_add_co_u32_e32 v34, vcc, s49, v20
	s_nop 1
	v_addc_co_u32_e32 v35, vcc, 0, v21, vcc
	v_add_co_u32_e32 v20, vcc, s50, v20
	s_nop 1
	v_addc_co_u32_e32 v21, vcc, 0, v21, vcc
	global_load_dword v22, v[22:23], off nt
	s_nop 0
	global_load_dword v23, v[24:25], off nt
	s_nop 0
	global_load_dword v24, v[26:27], off nt
	global_load_dword v25, v[28:29], off nt
	s_nop 0
	global_load_dword v26, v[30:31], off nt
	global_load_dword v27, v[32:33], off nt
	global_load_dword v28, v[34:35], off nt
	s_nop 0
	global_load_dword v20, v[20:21], off nt
	s_waitcnt vmcnt(30)
	ds_write2_b32 v7, v5, v38 offset1:66
	s_waitcnt vmcnt(28)
	ds_write2_b32 v7, v39, v40 offset0:132 offset1:198
	s_waitcnt vmcnt(26)
	ds_write2_b32 v13, v41, v43 offset0:8 offset1:74
	s_waitcnt vmcnt(24)
	ds_write2_b32 v13, v44, v45 offset0:140 offset1:206
	s_waitcnt vmcnt(22)
	ds_write2_b32 v14, v46, v47 offset0:16 offset1:82
	s_waitcnt vmcnt(20)
	ds_write2_b32 v14, v48, v49 offset0:148 offset1:214
	s_waitcnt vmcnt(18)
	ds_write2_b32 v15, v50, v51 offset0:24 offset1:90
	s_waitcnt vmcnt(16)
	ds_write2_b32 v15, v52, v53 offset0:156 offset1:222
	s_waitcnt vmcnt(14)
	ds_write2_b32 v16, v54, v55 offset0:32 offset1:98
	s_waitcnt vmcnt(12)
	ds_write2_b32 v16, v56, v57 offset0:164 offset1:230
	s_waitcnt vmcnt(10)
	ds_write2_b32 v17, v58, v59 offset0:40 offset1:106
	s_waitcnt vmcnt(8)
	ds_write2_b32 v17, v60, v36 offset0:172 offset1:238
	s_waitcnt vmcnt(6)
	ds_write2_b32 v18, v22, v23 offset0:48 offset1:114
	s_waitcnt vmcnt(4)
	ds_write2_b32 v18, v24, v25 offset0:180 offset1:246
	s_waitcnt vmcnt(2)
	ds_write2_b32 v19, v26, v27 offset0:56 offset1:122
	s_waitcnt vmcnt(0)
	ds_write2_b32 v19, v28, v20 offset0:188 offset1:254
	s_waitcnt lgkmcnt(0)
	ds_read2_b32 v[20:21], v9 offset1:33
	v_mov_b32_e32 v5, v3
	s_waitcnt lgkmcnt(0)
	v_cvt_pk_bf16_f32 v20, v20, v21
	ds_read2_b32 v[22:23], v9 offset0:66 offset1:99
	v_lshl_add_u64 v[26:27], s[6:7], 0, v[4:5]
	s_mov_b64 s[6:7], 0xd80000
	v_or_b32_e32 v5, s1, v8
	s_waitcnt lgkmcnt(0)
	v_cvt_pk_bf16_f32 v21, v22, v23
	ds_read2_b32 v[22:23], v9 offset0:132 offset1:165
	v_lshl_add_u64 v[26:27], v[26:27], 0, s[6:7]
	v_lshlrev_b32_e32 v28, 10, v5
	v_mov_b32_e32 v29, v3
	s_waitcnt lgkmcnt(0)
	v_cvt_pk_bf16_f32 v22, v22, v23
	ds_read2_b32 v[24:25], v9 offset0:198 offset1:231
	s_waitcnt lgkmcnt(0)
	v_cvt_pk_bf16_f32 v23, v24, v25
	v_lshl_add_u64 v[28:29], v[26:27], 0, v[28:29]
	ds_read2_b32 v[24:25], v9 offset0:8 offset1:41
	global_store_dwordx4 v[28:29], v[20:23], off
	v_or_b32_e32 v5, s1, v10
	v_lshlrev_b32_e32 v28, 10, v5
	s_waitcnt lgkmcnt(0)
	v_cvt_pk_bf16_f32 v20, v24, v25
	ds_read2_b32 v[22:23], v9 offset0:74 offset1:107
	s_waitcnt lgkmcnt(0)
	v_cvt_pk_bf16_f32 v21, v22, v23
	ds_read2_b32 v[22:23], v9 offset0:140 offset1:173
	v_mov_b32_e32 v29, v3
	s_waitcnt lgkmcnt(0)
	v_cvt_pk_bf16_f32 v22, v22, v23
	ds_read2_b32 v[24:25], v9 offset0:206 offset1:239
	s_waitcnt lgkmcnt(0)
	v_cvt_pk_bf16_f32 v23, v24, v25
	v_lshl_add_u64 v[28:29], v[26:27], 0, v[28:29]
	ds_read2_b32 v[24:25], v9 offset0:16 offset1:49
	global_store_dwordx4 v[28:29], v[20:23], off
	v_or_b32_e32 v5, s1, v11
	v_lshlrev_b32_e32 v28, 10, v5
	s_waitcnt lgkmcnt(0)
	v_cvt_pk_bf16_f32 v20, v24, v25
	ds_read2_b32 v[22:23], v9 offset0:82 offset1:115
	s_waitcnt lgkmcnt(0)
	v_cvt_pk_bf16_f32 v21, v22, v23
	ds_read2_b32 v[22:23], v9 offset0:148 offset1:181
	v_mov_b32_e32 v29, v3
	s_waitcnt lgkmcnt(0)
	v_cvt_pk_bf16_f32 v22, v22, v23
	ds_read2_b32 v[24:25], v9 offset0:214 offset1:247
	s_waitcnt lgkmcnt(0)
	v_cvt_pk_bf16_f32 v23, v24, v25
	v_lshl_add_u64 v[28:29], v[26:27], 0, v[28:29]
	ds_read2_b32 v[24:25], v9 offset0:24 offset1:57
	global_store_dwordx4 v[28:29], v[20:23], off
	v_or_b32_e32 v5, s1, v12
	s_waitcnt lgkmcnt(0)
	v_cvt_pk_bf16_f32 v20, v24, v25
	ds_read2_b32 v[22:23], v9 offset0:90 offset1:123
	s_waitcnt lgkmcnt(0)
	v_cvt_pk_bf16_f32 v21, v22, v23
	ds_read2_b32 v[22:23], v9 offset0:156 offset1:189
	s_waitcnt lgkmcnt(0)
	v_cvt_pk_bf16_f32 v22, v22, v23
	ds_read2_b32 v[24:25], v9 offset0:222 offset1:255
	s_waitcnt lgkmcnt(0)
	v_cvt_pk_bf16_f32 v23, v24, v25
	v_lshlrev_b32_e32 v24, 10, v5
	v_mov_b32_e32 v25, v3
	v_lshl_add_u64 v[24:25], v[26:27], 0, v[24:25]
	global_store_dwordx4 v[24:25], v[20:23], off
	s_waitcnt lgkmcnt(0)

.LBB0_37:
	s_andn2_b64 vcc, exec, s[6:7]
	s_cbranch_vccnz .LBB0_39
	v_readlane_b32 s68, v248, 2
	s_mul_i32 s6, s0, 0x300000
	v_readlane_b32 s72, v248, 6
	s_mul_hi_i32 s1, s0, 0x300000
	v_readlane_b32 s73, v248, 7
	s_add_u32 s7, s72, s6
	s_addc_u32 s9, s73, s1
	s_add_i32 s1, s58, 0xf4c0
	s_and_b32 s6, s1, 0xffff
	s_mul_i32 s6, s6, 0xaaab
	s_lshr_b32 s6, s6, 21
	s_mul_i32 s8, s6, 48
	s_sub_i32 s1, s1, s8
	s_lshl_b32 s1, s1, 5
	s_and_b32 s1, s1, 0xffe0
	s_lshl_b32 s8, s1, 2
	s_add_u32 s8, s7, s8
	v_lshl_or_b32 v5, s6, 6, v6
	s_addc_u32 s9, s9, 0
	v_lshl_add_u64 v[20:21], s[8:9], 0, v[2:3]
	v_mul_u32_u24_e32 v22, 0x1800, v5
	v_mov_b32_e32 v23, v3
	v_lshl_add_u64 v[20:21], v[20:21], 0, v[22:23]
	s_movk_i32 s7, 0x3000
	v_add_co_u32_e32 v22, vcc, s7, v20
	s_movk_i32 s7, 0x6000
	s_nop 0
	v_addc_co_u32_e32 v23, vcc, 0, v21, vcc
	v_add_co_u32_e32 v24, vcc, s7, v20
	s_mov_b32 s7, 0x9000
	s_nop 0
	v_addc_co_u32_e32 v25, vcc, 0, v21, vcc
	v_add_co_u32_e32 v26, vcc, s7, v20
	s_mov_b32 s7, 0xf000
	s_nop 0
	v_addc_co_u32_e32 v27, vcc, 0, v21, vcc
	v_add_co_u32_e32 v28, vcc, s18, v20
	s_lshl_b32 s6, s6, 7
	s_nop 0
	v_addc_co_u32_e32 v29, vcc, 0, v21, vcc
	v_add_co_u32_e32 v30, vcc, s7, v20
	s_mov_b32 s7, 0x12000
	s_nop 0
	v_addc_co_u32_e32 v31, vcc, 0, v21, vcc
	v_add_co_u32_e32 v32, vcc, s7, v20
	s_mov_b32 s7, 0x15000
	s_nop 0
	v_addc_co_u32_e32 v33, vcc, 0, v21, vcc
	v_add_co_u32_e32 v34, vcc, s7, v20
	s_mov_b32 s7, 0x1b000
	s_nop 0
	v_addc_co_u32_e32 v35, vcc, 0, v21, vcc
	global_load_dword v5, v[20:21], off nt
	global_load_dword v38, v[22:23], off nt
	global_load_dword v39, v[24:25], off nt
	global_load_dword v40, v[26:27], off nt
	global_load_dword v41, v[28:29], off nt
	global_load_dword v43, v[30:31], off nt
	global_load_dword v44, v[32:33], off nt
	global_load_dword v45, v[34:35], off nt
	v_add_co_u32_e32 v22, vcc, s21, v20
	s_add_u32 s6, s56, s6
	s_nop 0
	v_addc_co_u32_e32 v23, vcc, 0, v21, vcc
	v_add_co_u32_e32 v24, vcc, s7, v20
	s_mov_b32 s7, 0x1e000
	s_nop 0
	v_addc_co_u32_e32 v25, vcc, 0, v21, vcc
	v_add_co_u32_e32 v26, vcc, s7, v20
	s_mov_b32 s7, 0x2a000
	s_nop 0
	v_addc_co_u32_e32 v27, vcc, 0, v21, vcc
	v_add_co_u32_e32 v28, vcc, s51, v20
	v_readlane_b32 s69, v248, 3
	s_nop 0
	v_addc_co_u32_e32 v29, vcc, 0, v21, vcc
	v_add_co_u32_e32 v30, vcc, s24, v20
	v_readlane_b32 s70, v248, 4
	s_nop 0
	v_addc_co_u32_e32 v31, vcc, 0, v21, vcc
	v_add_co_u32_e32 v32, vcc, s52, v20
	v_readlane_b32 s71, v248, 5
	s_nop 0
	v_addc_co_u32_e32 v33, vcc, 0, v21, vcc
	v_add_co_u32_e32 v34, vcc, s7, v20
	s_mov_b32 s7, 0x33000
	s_nop 0
	v_addc_co_u32_e32 v35, vcc, 0, v21, vcc
	v_add_co_u32_e32 v36, vcc, s53, v20
	v_readlane_b32 s74, v248, 8
	s_nop 0
	v_addc_co_u32_e32 v37, vcc, 0, v21, vcc
	global_load_dword v46, v[22:23], off nt
	global_load_dword v47, v[24:25], off nt
	global_load_dword v48, v[26:27], off nt
	global_load_dword v49, v[28:29], off nt
	global_load_dword v50, v[30:31], off nt
	global_load_dword v51, v[32:33], off nt
	global_load_dword v52, v[34:35], off nt
	global_load_dword v53, v[36:37], off nt
	v_add_co_u32_e32 v22, vcc, s27, v20
	v_readlane_b32 s75, v248, 9
	s_nop 0
	v_addc_co_u32_e32 v23, vcc, 0, v21, vcc
	v_add_co_u32_e32 v24, vcc, s7, v20
	s_mov_b32 s7, 0x36000
	s_nop 0
	v_addc_co_u32_e32 v25, vcc, 0, v21, vcc
	v_add_co_u32_e32 v26, vcc, s7, v20
	s_mov_b32 s7, 0x39000
	s_nop 0
	v_addc_co_u32_e32 v27, vcc, 0, v21, vcc
	v_add_co_u32_e32 v28, vcc, s7, v20
	s_mov_b32 s7, 0x3f000
	s_nop 0
	v_addc_co_u32_e32 v29, vcc, 0, v21, vcc
	v_add_co_u32_e32 v30, vcc, s30, v20
	v_readlane_b32 s76, v248, 10
	s_nop 0
	v_addc_co_u32_e32 v31, vcc, 0, v21, vcc
	v_add_co_u32_e32 v32, vcc, s7, v20
	s_mov_b32 s7, 0x42000
	s_nop 0
	v_addc_co_u32_e32 v33, vcc, 0, v21, vcc
	v_add_co_u32_e32 v34, vcc, s7, v20
	s_mov_b32 s7, 0x45000
	s_nop 0
	v_addc_co_u32_e32 v35, vcc, 0, v21, vcc
	v_add_co_u32_e32 v36, vcc, s7, v20
	s_mov_b32 s7, 0x4b000
	s_nop 0
	v_addc_co_u32_e32 v37, vcc, 0, v21, vcc
	global_load_dword v54, v[22:23], off nt
	global_load_dword v55, v[24:25], off nt
	global_load_dword v56, v[26:27], off nt
	global_load_dword v57, v[28:29], off nt
	global_load_dword v58, v[30:31], off nt
	global_load_dword v59, v[32:33], off nt
	global_load_dword v60, v[34:35], off nt
	s_nop 0
	global_load_dword v36, v[36:37], off nt
	v_add_co_u32_e32 v22, vcc, s37, v20
	v_readlane_b32 s77, v248, 11
	s_nop 0
	v_addc_co_u32_e32 v23, vcc, 0, v21, vcc
	v_add_co_u32_e32 v24, vcc, s7, v20
	s_mov_b32 s7, 0x51000
	s_nop 0
	v_addc_co_u32_e32 v25, vcc, 0, v21, vcc
	v_add_co_u32_e32 v26, vcc, s54, v20
	v_readlane_b32 s78, v248, 12
	s_nop 0
	v_addc_co_u32_e32 v27, vcc, 0, v21, vcc
	v_add_co_u32_e32 v28, vcc, s7, v20
	s_mov_b32 s7, 0x57000
	s_nop 0
	v_addc_co_u32_e32 v29, vcc, 0, v21, vcc
	v_add_co_u32_e32 v30, vcc, s40, v20
	v_readlane_b32 s79, v248, 13
	s_nop 0
	v_addc_co_u32_e32 v31, vcc, 0, v21, vcc
	v_add_co_u32_e32 v32, vcc, s7, v20
	s_mov_b32 s7, 0x5d000
	s_nop 0
	v_addc_co_u32_e32 v33, vcc, 0, v21, vcc
	v_add_co_u32_e32 v34, vcc, s55, v20
	v_readlane_b32 s80, v248, 14
	s_nop 0
	v_addc_co_u32_e32 v35, vcc, 0, v21, vcc
	v_add_co_u32_e32 v20, vcc, s7, v20
	s_addc_u32 s7, s57, 0
	s_nop 0
	v_addc_co_u32_e32 v21, vcc, 0, v21, vcc
	global_load_dword v22, v[22:23], off nt
	s_nop 0
	global_load_dword v23, v[24:25], off nt
	s_nop 0
	global_load_dword v24, v[26:27], off nt
	global_load_dword v25, v[28:29], off nt
	s_nop 0
	global_load_dword v26, v[30:31], off nt
	global_load_dword v27, v[32:33], off nt
	global_load_dword v28, v[34:35], off nt
	s_nop 0
	global_load_dword v20, v[20:21], off nt
	s_waitcnt vmcnt(30)
	ds_write2_b32 v7, v5, v38 offset1:66
	s_waitcnt vmcnt(28)
	ds_write2_b32 v7, v39, v40 offset0:132 offset1:198
	s_waitcnt vmcnt(26)
	ds_write2_b32 v13, v41, v43 offset0:8 offset1:74
	s_waitcnt vmcnt(24)
	ds_write2_b32 v13, v44, v45 offset0:140 offset1:206
	s_waitcnt vmcnt(22)
	ds_write2_b32 v14, v46, v47 offset0:16 offset1:82
	s_waitcnt vmcnt(20)
	ds_write2_b32 v14, v48, v49 offset0:148 offset1:214
	s_waitcnt vmcnt(18)
	ds_write2_b32 v15, v50, v51 offset0:24 offset1:90
	s_waitcnt vmcnt(16)
	ds_write2_b32 v15, v52, v53 offset0:156 offset1:222
	s_waitcnt vmcnt(14)
	ds_write2_b32 v16, v54, v55 offset0:32 offset1:98
	s_waitcnt vmcnt(12)
	ds_write2_b32 v16, v56, v57 offset0:164 offset1:230
	s_waitcnt vmcnt(10)
	ds_write2_b32 v17, v58, v59 offset0:40 offset1:106
	s_waitcnt vmcnt(8)
	ds_write2_b32 v17, v60, v36 offset0:172 offset1:238
	s_waitcnt vmcnt(6)
	ds_write2_b32 v18, v22, v23 offset0:48 offset1:114
	s_waitcnt vmcnt(4)
	ds_write2_b32 v18, v24, v25 offset0:180 offset1:246
	s_waitcnt vmcnt(2)
	ds_write2_b32 v19, v26, v27 offset0:56 offset1:122
	s_waitcnt vmcnt(0)
	ds_write2_b32 v19, v28, v20 offset0:188 offset1:254
	s_waitcnt lgkmcnt(0)
	ds_read2_b32 v[20:21], v9 offset1:33
	v_mov_b32_e32 v5, v3
	s_waitcnt lgkmcnt(0)
	v_cvt_pk_bf16_f32 v20, v20, v21
	ds_read2_b32 v[22:23], v9 offset0:66 offset1:99
	v_lshl_add_u64 v[26:27], s[6:7], 0, v[4:5]
	s_mov_b64 s[6:7], 0xc00000
	v_or_b32_e32 v5, s1, v8
	s_waitcnt lgkmcnt(0)
	v_cvt_pk_bf16_f32 v21, v22, v23
	ds_read2_b32 v[22:23], v9 offset0:132 offset1:165
	v_lshl_add_u64 v[26:27], v[26:27], 0, s[6:7]
	v_lshlrev_b32_e32 v28, 10, v5
	v_mov_b32_e32 v29, v3
	s_waitcnt lgkmcnt(0)
	v_cvt_pk_bf16_f32 v22, v22, v23
	ds_read2_b32 v[24:25], v9 offset0:198 offset1:231
	s_waitcnt lgkmcnt(0)
	v_cvt_pk_bf16_f32 v23, v24, v25
	v_lshl_add_u64 v[28:29], v[26:27], 0, v[28:29]
	ds_read2_b32 v[24:25], v9 offset0:8 offset1:41
	global_store_dwordx4 v[28:29], v[20:23], off
	v_or_b32_e32 v5, s1, v10
	v_lshlrev_b32_e32 v28, 10, v5
	s_waitcnt lgkmcnt(0)
	v_cvt_pk_bf16_f32 v20, v24, v25
	ds_read2_b32 v[22:23], v9 offset0:74 offset1:107
	s_waitcnt lgkmcnt(0)
	v_cvt_pk_bf16_f32 v21, v22, v23
	ds_read2_b32 v[22:23], v9 offset0:140 offset1:173
	v_mov_b32_e32 v29, v3
	s_waitcnt lgkmcnt(0)
	v_cvt_pk_bf16_f32 v22, v22, v23
	ds_read2_b32 v[24:25], v9 offset0:206 offset1:239
	s_waitcnt lgkmcnt(0)
	v_cvt_pk_bf16_f32 v23, v24, v25
	v_lshl_add_u64 v[28:29], v[26:27], 0, v[28:29]
	ds_read2_b32 v[24:25], v9 offset0:16 offset1:49
	global_store_dwordx4 v[28:29], v[20:23], off
	v_or_b32_e32 v5, s1, v11
	v_lshlrev_b32_e32 v28, 10, v5
	s_waitcnt lgkmcnt(0)
	v_cvt_pk_bf16_f32 v20, v24, v25
	ds_read2_b32 v[22:23], v9 offset0:82 offset1:115
	s_waitcnt lgkmcnt(0)
	v_cvt_pk_bf16_f32 v21, v22, v23
	ds_read2_b32 v[22:23], v9 offset0:148 offset1:181
	v_mov_b32_e32 v29, v3
	s_waitcnt lgkmcnt(0)
	v_cvt_pk_bf16_f32 v22, v22, v23
	ds_read2_b32 v[24:25], v9 offset0:214 offset1:247
	s_waitcnt lgkmcnt(0)
	v_cvt_pk_bf16_f32 v23, v24, v25
	v_lshl_add_u64 v[28:29], v[26:27], 0, v[28:29]
	ds_read2_b32 v[24:25], v9 offset0:24 offset1:57
	global_store_dwordx4 v[28:29], v[20:23], off
	v_or_b32_e32 v5, s1, v12
	v_readlane_b32 s81, v248, 15
	s_waitcnt lgkmcnt(0)
	v_cvt_pk_bf16_f32 v20, v24, v25
	ds_read2_b32 v[22:23], v9 offset0:90 offset1:123
	s_waitcnt lgkmcnt(0)
	v_cvt_pk_bf16_f32 v21, v22, v23
	ds_read2_b32 v[22:23], v9 offset0:156 offset1:189
	s_waitcnt lgkmcnt(0)
	v_cvt_pk_bf16_f32 v22, v22, v23
	ds_read2_b32 v[24:25], v9 offset0:222 offset1:255
	s_waitcnt lgkmcnt(0)
	v_cvt_pk_bf16_f32 v23, v24, v25
	v_lshlrev_b32_e32 v24, 10, v5
	v_mov_b32_e32 v25, v3
	v_lshl_add_u64 v[24:25], v[26:27], 0, v[24:25]
	global_store_dwordx4 v[24:25], v[20:23], off
	s_waitcnt lgkmcnt(0)
	v_readlane_b32 s82, v248, 16
	v_readlane_b32 s83, v248, 17

.LBB0_41:
	s_mul_hi_i32 s1, s0, 0x1680000
	s_mul_i32 s0, s0, 0x1680000
	v_readlane_b32 s68, v248, 2
	v_readlane_b32 s69, v248, 3
	s_add_u32 s7, s68, s0
	s_mul_i32 s0, s58, 0x2d83
	s_addc_u32 s59, s69, s1
	s_lshr_b32 s1, s0, 31
	s_ashr_i32 s0, s0, 20
	s_add_i32 s0, s0, s1
	s_mul_i32 s1, s0, 0x5a
	s_sub_i32 s1, s58, s1
	s_sext_i32_i16 s1, s1
	s_lshl_b32 s6, s0, 6
	s_lshl_b32 s0, s1, 5
	s_ashr_i32 s1, s0, 31
	s_lshl_b64 s[8:9], s[0:1], 2
	v_or_b32_e32 v5, s6, v6
	s_add_u32 s8, s7, s8
	s_addc_u32 s9, s59, s9
	v_mul_i32_i24_e32 v22, 0x2d00, v5
	v_lshl_add_u64 v[20:21], s[8:9], 0, v[2:3]
	v_ashrrev_i32_e32 v23, 31, v22
	v_lshl_add_u64 v[20:21], v[20:21], 0, v[22:23]
	s_movk_i32 s1, 0x5000
	v_add_co_u32_e32 v22, vcc, s1, v20
	s_mov_b32 s1, 0xb000
	s_nop 0
	v_addc_co_u32_e32 v23, vcc, 0, v21, vcc
	v_add_co_u32_e32 v24, vcc, s1, v20
	s_mov_b32 s1, 0x16000
	s_nop 0
	v_addc_co_u32_e32 v25, vcc, 0, v21, vcc
	v_add_co_u32_e32 v26, vcc, s19, v20
	s_ashr_i32 s7, s6, 31
	s_nop 0
	v_addc_co_u32_e32 v27, vcc, 0, v21, vcc
	v_add_co_u32_e32 v28, vcc, s1, v20
	s_mov_b32 s1, 0x32000
	s_nop 0
	v_addc_co_u32_e32 v29, vcc, 0, v21, vcc
	v_add_co_u32_e32 v30, vcc, s22, v20
	s_lshl_b64 s[6:7], s[6:7], 1
	s_nop 0
	v_addc_co_u32_e32 v31, vcc, 0, v21, vcc
	v_add_co_u32_e32 v32, vcc, s51, v20
	s_add_u32 s6, s56, s6
	s_nop 0
	v_addc_co_u32_e32 v33, vcc, 0, v21, vcc
	v_add_co_u32_e32 v34, vcc, s52, v20
	s_addc_u32 s7, s57, s7
	s_nop 0
	v_addc_co_u32_e32 v35, vcc, 0, v21, vcc
	global_load_dword v5, v[20:21], off nt
	global_load_dword v38, v[22:23], off offset:2560 nt
	global_load_dword v39, v[24:25], off offset:1024 nt
	global_load_dword v40, v[26:27], off offset:3584 nt
	global_load_dword v41, v[28:29], off offset:2048 nt
	global_load_dword v43, v[30:31], off offset:512 nt
	global_load_dword v44, v[32:33], off offset:3072 nt
	global_load_dword v45, v[34:35], off offset:1536 nt
	v_add_co_u32_e32 v22, vcc, s53, v20
	v_readlane_b32 s70, v248, 4
	s_nop 0
	v_addc_co_u32_e32 v23, vcc, 0, v21, vcc
	v_add_co_u32_e32 v24, vcc, s1, v20
	s_mov_b32 s1, 0x3d000
	s_nop 0
	v_addc_co_u32_e32 v25, vcc, 0, v21, vcc
	v_add_co_u32_e32 v26, vcc, s29, v20
	v_readlane_b32 s71, v248, 5
	s_nop 0
	v_addc_co_u32_e32 v27, vcc, 0, v21, vcc
	v_add_co_u32_e32 v28, vcc, s1, v20
	s_mov_b32 s1, 0x43000
	s_nop 0
	v_addc_co_u32_e32 v29, vcc, 0, v21, vcc
	v_add_co_u32_e32 v30, vcc, s1, v20
	s_mov_b32 s1, 0x49000
	s_nop 0
	v_addc_co_u32_e32 v31, vcc, 0, v21, vcc
	v_add_co_u32_e32 v32, vcc, s1, v20
	s_mov_b32 s1, 0x5f000
	s_nop 0
	v_addc_co_u32_e32 v33, vcc, 0, v21, vcc
	v_add_co_u32_e32 v34, vcc, s54, v20
	v_readlane_b32 s72, v248, 6
	s_nop 0
	v_addc_co_u32_e32 v35, vcc, 0, v21, vcc
	v_add_co_u32_e32 v36, vcc, s40, v20
	v_readlane_b32 s73, v248, 7
	s_nop 0
	v_addc_co_u32_e32 v37, vcc, 0, v21, vcc
	global_load_dword v46, v[22:23], off nt
	global_load_dword v47, v[24:25], off offset:2560 nt
	global_load_dword v48, v[26:27], off offset:1024 nt
	global_load_dword v49, v[28:29], off offset:3584 nt
	global_load_dword v50, v[30:31], off offset:2048 nt
	global_load_dword v51, v[32:33], off offset:512 nt
	global_load_dword v52, v[34:35], off offset:3072 nt
	global_load_dword v53, v[36:37], off offset:1536 nt
	v_add_co_u32_e32 v22, vcc, s55, v20
	v_readlane_b32 s74, v248, 8
	s_nop 0
	v_addc_co_u32_e32 v23, vcc, 0, v21, vcc
	v_add_co_u32_e32 v24, vcc, s1, v20
	s_mov_b32 s1, 0x65000
	s_nop 0
	v_addc_co_u32_e32 v25, vcc, 0, v21, vcc
	v_add_co_u32_e32 v26, vcc, s1, v20
	s_mov_b32 s1, 0x6a000
	s_nop 0
	v_addc_co_u32_e32 v27, vcc, 0, v21, vcc
	v_add_co_u32_e32 v28, vcc, s1, v20
	s_mov_b32 s1, 0x76000
	s_nop 0
	v_addc_co_u32_e32 v29, vcc, 0, v21, vcc
	v_add_co_u32_e32 v30, vcc, s47, v20
	v_readlane_b32 s75, v248, 9
	s_nop 0
	v_addc_co_u32_e32 v31, vcc, 0, v21, vcc
	v_add_co_u32_e32 v32, vcc, s1, v20
	s_mov_b32 s1, 0x7b000
	s_nop 0
	v_addc_co_u32_e32 v33, vcc, 0, v21, vcc
	v_add_co_u32_e32 v34, vcc, s1, v20
	s_mov_b32 s1, 0x81000
	s_nop 0
	v_addc_co_u32_e32 v35, vcc, 0, v21, vcc
	v_add_co_u32_e32 v36, vcc, s1, v20
	s_mov_b32 s1, 0x87000
	s_nop 0
	v_addc_co_u32_e32 v37, vcc, 0, v21, vcc
	global_load_dword v54, v[22:23], off nt
	global_load_dword v55, v[24:25], off offset:2560 nt
	global_load_dword v56, v[26:27], off offset:1024 nt
	global_load_dword v57, v[28:29], off offset:3584 nt
	global_load_dword v58, v[30:31], off offset:2048 nt
	global_load_dword v59, v[32:33], off offset:512 nt
	global_load_dword v60, v[34:35], off offset:3072 nt
	s_nop 0
	global_load_dword v36, v[36:37], off offset:1536 nt
	v_add_co_u32_e32 v22, vcc, s1, v20
	s_mov_b32 s1, 0x8c000
	s_nop 0
	v_addc_co_u32_e32 v23, vcc, 0, v21, vcc
	v_add_co_u32_e32 v24, vcc, s1, v20
	s_mov_b32 s1, 0x92000
	s_nop 0
	v_addc_co_u32_e32 v25, vcc, 0, v21, vcc
	v_add_co_u32_e32 v26, vcc, s1, v20
	s_mov_b32 s1, 0x97000
	s_nop 0
	v_addc_co_u32_e32 v27, vcc, 0, v21, vcc
	v_add_co_u32_e32 v28, vcc, s1, v20
	s_mov_b32 s1, 0x9d000
	s_nop 0
	v_addc_co_u32_e32 v29, vcc, 0, v21, vcc
	v_add_co_u32_e32 v30, vcc, s1, v20
	s_mov_b32 s1, 0xa3000
	s_nop 0
	v_addc_co_u32_e32 v31, vcc, 0, v21, vcc
	v_add_co_u32_e32 v32, vcc, s1, v20
	s_mov_b32 s1, 0xa8000
	s_nop 0
	v_addc_co_u32_e32 v33, vcc, 0, v21, vcc
	v_add_co_u32_e32 v34, vcc, s1, v20
	s_mov_b32 s1, 0xae000
	s_nop 0
	v_addc_co_u32_e32 v35, vcc, 0, v21, vcc
	v_add_co_u32_e32 v20, vcc, s1, v20
	v_readlane_b32 s76, v248, 10
	s_nop 0
	v_addc_co_u32_e32 v21, vcc, 0, v21, vcc
	global_load_dword v22, v[22:23], off nt
	s_nop 0
	global_load_dword v23, v[24:25], off offset:2560 nt
	s_nop 0
	global_load_dword v24, v[26:27], off offset:1024 nt
	global_load_dword v25, v[28:29], off offset:3584 nt
	s_nop 0
	global_load_dword v26, v[30:31], off offset:2048 nt
	global_load_dword v27, v[32:33], off offset:512 nt
	global_load_dword v28, v[34:35], off offset:3072 nt
	s_nop 0
	global_load_dword v20, v[20:21], off offset:1536 nt
	s_waitcnt vmcnt(30)
	ds_write2_b32 v7, v5, v38 offset1:66
	s_waitcnt vmcnt(28)
	ds_write2_b32 v7, v39, v40 offset0:132 offset1:198
	s_waitcnt vmcnt(26)
	ds_write2_b32 v13, v41, v43 offset0:8 offset1:74
	s_waitcnt vmcnt(24)
	ds_write2_b32 v13, v44, v45 offset0:140 offset1:206
	s_waitcnt vmcnt(22)
	ds_write2_b32 v14, v46, v47 offset0:16 offset1:82
	s_waitcnt vmcnt(20)
	ds_write2_b32 v14, v48, v49 offset0:148 offset1:214
	s_waitcnt vmcnt(18)
	ds_write2_b32 v15, v50, v51 offset0:24 offset1:90
	s_waitcnt vmcnt(16)
	ds_write2_b32 v15, v52, v53 offset0:156 offset1:222
	s_waitcnt vmcnt(14)
	ds_write2_b32 v16, v54, v55 offset0:32 offset1:98
	s_waitcnt vmcnt(12)
	ds_write2_b32 v16, v56, v57 offset0:164 offset1:230
	s_waitcnt vmcnt(10)
	ds_write2_b32 v17, v58, v59 offset0:40 offset1:106
	s_waitcnt vmcnt(8)
	ds_write2_b32 v17, v60, v36 offset0:172 offset1:238
	s_waitcnt vmcnt(6)
	ds_write2_b32 v18, v22, v23 offset0:48 offset1:114
	s_waitcnt vmcnt(4)
	ds_write2_b32 v18, v24, v25 offset0:180 offset1:246
	s_waitcnt vmcnt(2)
	ds_write2_b32 v19, v26, v27 offset0:56 offset1:122
	s_waitcnt vmcnt(0)
	ds_write2_b32 v19, v28, v20 offset0:188 offset1:254
	s_waitcnt lgkmcnt(0)
	ds_read2_b32 v[20:21], v9 offset1:33
	s_waitcnt lgkmcnt(0)
	v_cvt_pk_bf16_f32 v20, v20, v21
	ds_read2_b32 v[22:23], v9 offset0:66 offset1:99
	s_waitcnt lgkmcnt(0)
	v_cvt_pk_bf16_f32 v21, v22, v23
	ds_read2_b32 v[22:23], v9 offset0:132 offset1:165
	s_waitcnt lgkmcnt(0)
	v_cvt_pk_bf16_f32 v22, v22, v23
	ds_read2_b32 v[24:25], v9 offset0:198 offset1:231
	s_waitcnt lgkmcnt(0)
	v_cvt_pk_bf16_f32 v23, v24, v25
	v_or_b32_e32 v24, s0, v8
	v_mov_b32_e32 v5, v3
	v_ashrrev_i32_e32 v25, 31, v24
	v_lshl_add_u64 v[26:27], s[6:7], 0, v[4:5]
	v_lshlrev_b64 v[24:25], 12, v[24:25]
	v_lshl_add_u64 v[24:25], v[26:27], 0, v[24:25]
	ds_read2_b32 v[28:29], v9 offset0:8 offset1:41
	global_store_dwordx4 v[24:25], v[20:23], off
	v_readlane_b32 s77, v248, 11
	v_readlane_b32 s78, v248, 12
	s_waitcnt lgkmcnt(0)
	v_cvt_pk_bf16_f32 v20, v28, v29
	ds_read2_b32 v[22:23], v9 offset0:74 offset1:107
	s_waitcnt lgkmcnt(0)
	v_cvt_pk_bf16_f32 v21, v22, v23
	ds_read2_b32 v[22:23], v9 offset0:140 offset1:173
	s_waitcnt lgkmcnt(0)
	v_cvt_pk_bf16_f32 v22, v22, v23
	ds_read2_b32 v[24:25], v9 offset0:206 offset1:239
	s_waitcnt lgkmcnt(0)
	v_cvt_pk_bf16_f32 v23, v24, v25
	v_or_b32_e32 v24, s0, v10
	v_ashrrev_i32_e32 v25, 31, v24
	v_lshlrev_b64 v[24:25], 12, v[24:25]
	v_lshl_add_u64 v[24:25], v[26:27], 0, v[24:25]
	ds_read2_b32 v[28:29], v9 offset0:16 offset1:49
	global_store_dwordx4 v[24:25], v[20:23], off
	v_readlane_b32 s79, v248, 13
	v_readlane_b32 s80, v248, 14
	s_waitcnt lgkmcnt(0)
	v_cvt_pk_bf16_f32 v20, v28, v29
	ds_read2_b32 v[22:23], v9 offset0:82 offset1:115
	s_waitcnt lgkmcnt(0)
	v_cvt_pk_bf16_f32 v21, v22, v23
	ds_read2_b32 v[22:23], v9 offset0:148 offset1:181
	s_waitcnt lgkmcnt(0)
	v_cvt_pk_bf16_f32 v22, v22, v23
	ds_read2_b32 v[24:25], v9 offset0:214 offset1:247
	s_waitcnt lgkmcnt(0)
	v_cvt_pk_bf16_f32 v23, v24, v25
	v_or_b32_e32 v24, s0, v11
	v_ashrrev_i32_e32 v25, 31, v24
	v_lshlrev_b64 v[24:25], 12, v[24:25]
	v_lshl_add_u64 v[24:25], v[26:27], 0, v[24:25]
	ds_read2_b32 v[28:29], v9 offset0:24 offset1:57
	global_store_dwordx4 v[24:25], v[20:23], off
	v_readlane_b32 s81, v248, 15
	v_readlane_b32 s82, v248, 16
	s_waitcnt lgkmcnt(0)
	v_cvt_pk_bf16_f32 v20, v28, v29
	ds_read2_b32 v[22:23], v9 offset0:90 offset1:123
	s_waitcnt lgkmcnt(0)
	v_cvt_pk_bf16_f32 v21, v22, v23
	ds_read2_b32 v[22:23], v9 offset0:156 offset1:189
	s_waitcnt lgkmcnt(0)
	v_cvt_pk_bf16_f32 v22, v22, v23
	ds_read2_b32 v[24:25], v9 offset0:222 offset1:255
	s_waitcnt lgkmcnt(0)
	v_cvt_pk_bf16_f32 v23, v24, v25
	v_or_b32_e32 v24, s0, v12
	v_ashrrev_i32_e32 v25, 31, v24
	v_lshlrev_b64 v[24:25], 12, v[24:25]
	v_lshl_add_u64 v[24:25], v[26:27], 0, v[24:25]
	global_store_dwordx4 v[24:25], v[20:23], off
	s_waitcnt lgkmcnt(0)
	v_readlane_b32 s83, v248, 17
	s_branch .LBB0_21

.Ltr_a_m0_loop:
	s_cmp_ge_u32 s60, s61
	s_cbranch_scc1 .Ltr_a_m0_end
	s_mul_i32 s70, s60, 1366
	s_lshr_b32 s70, s70, 16
	s_mul_i32 s69, s70, 48
	s_sub_u32 s71, s60, s69
	s_mul_i32 s69, s70, 0x60000
	s_lshl_b32 s80, s71, 7
	s_add_u32 s69, s69, s80
	s_add_u32 s72, s64, s69
	s_addc_u32 s73, s65, 0
	s_mul_i32 s69, s71, 0x8000
	s_lshl_b32 s80, s70, 7
	s_add_u32 s69, s69, s80
	s_add_u32 s74, s66, s69
	s_addc_u32 s75, s67, 0
	v_mov_b32_e32 v3, v2
	global_load_dword v4, v3, s[72:73] nt
	v_add_u32_e32 v3, s68, v3
	global_load_dword v5, v3, s[72:73] nt
	v_add_u32_e32 v3, s68, v3
	global_load_dword v6, v3, s[72:73] nt
	v_add_u32_e32 v3, s68, v3
	global_load_dword v7, v3, s[72:73] nt
	v_add_u32_e32 v3, s68, v3
	global_load_dword v8, v3, s[72:73] nt
	v_add_u32_e32 v3, s68, v3
	global_load_dword v9, v3, s[72:73] nt
	v_add_u32_e32 v3, s68, v3
	global_load_dword v10, v3, s[72:73] nt
	v_add_u32_e32 v3, s68, v3
	global_load_dword v11, v3, s[72:73] nt
	v_add_u32_e32 v3, s68, v3
	global_load_dword v12, v3, s[72:73] nt
	v_add_u32_e32 v3, s68, v3
	global_load_dword v13, v3, s[72:73] nt
	v_add_u32_e32 v3, s68, v3
	global_load_dword v14, v3, s[72:73] nt
	v_add_u32_e32 v3, s68, v3
	global_load_dword v15, v3, s[72:73] nt
	v_add_u32_e32 v3, s68, v3
	global_load_dword v16, v3, s[72:73] nt
	v_add_u32_e32 v3, s68, v3
	global_load_dword v17, v3, s[72:73] nt
	v_add_u32_e32 v3, s68, v3
	global_load_dword v18, v3, s[72:73] nt
	v_add_u32_e32 v3, s68, v3
	global_load_dword v19, v3, s[72:73] nt
	v_add_u32_e32 v3, s68, v3
	global_load_dword v20, v3, s[72:73] nt
	v_add_u32_e32 v3, s68, v3
	global_load_dword v21, v3, s[72:73] nt
	v_add_u32_e32 v3, s68, v3
	global_load_dword v22, v3, s[72:73] nt
	v_add_u32_e32 v3, s68, v3
	global_load_dword v23, v3, s[72:73] nt
	v_add_u32_e32 v3, s68, v3
	global_load_dword v24, v3, s[72:73] nt
	v_add_u32_e32 v3, s68, v3
	global_load_dword v25, v3, s[72:73] nt
	v_add_u32_e32 v3, s68, v3
	global_load_dword v26, v3, s[72:73] nt
	v_add_u32_e32 v3, s68, v3
	global_load_dword v27, v3, s[72:73] nt
	v_add_u32_e32 v3, s68, v3
	global_load_dword v28, v3, s[72:73] nt
	v_add_u32_e32 v3, s68, v3
	global_load_dword v29, v3, s[72:73] nt
	v_add_u32_e32 v3, s68, v3
	global_load_dword v30, v3, s[72:73] nt
	v_add_u32_e32 v3, s68, v3
	global_load_dword v31, v3, s[72:73] nt
	v_add_u32_e32 v3, s68, v3
	global_load_dword v32, v3, s[72:73] nt
	v_add_u32_e32 v3, s68, v3
	global_load_dword v33, v3, s[72:73] nt
	v_add_u32_e32 v3, s68, v3
	global_load_dword v34, v3, s[72:73] nt
	v_add_u32_e32 v3, s68, v3
	global_load_dword v35, v3, s[72:73] nt
	s_waitcnt vmcnt(0)
	v_permlane32_swap_b32_e32 v4, v20
	v_permlane32_swap_b32_e32 v5, v21
	v_permlane32_swap_b32_e32 v6, v22
	v_permlane32_swap_b32_e32 v7, v23
	v_permlane32_swap_b32_e32 v8, v24
	v_permlane32_swap_b32_e32 v9, v25
	v_permlane32_swap_b32_e32 v10, v26
	v_permlane32_swap_b32_e32 v11, v27
	v_permlane32_swap_b32_e32 v12, v28
	v_permlane32_swap_b32_e32 v13, v29
	v_permlane32_swap_b32_e32 v14, v30
	v_permlane32_swap_b32_e32 v15, v31
	v_permlane32_swap_b32_e32 v16, v32
	v_permlane32_swap_b32_e32 v17, v33
	v_permlane32_swap_b32_e32 v18, v34
	v_permlane32_swap_b32_e32 v19, v35
	v_cvt_pk_bf16_f32 v36, v4, v20
	v_cvt_pk_bf16_f32 v37, v5, v21
	v_cvt_pk_bf16_f32 v38, v6, v22
	v_cvt_pk_bf16_f32 v39, v7, v23
	v_cvt_pk_bf16_f32 v40, v8, v24
	v_cvt_pk_bf16_f32 v41, v9, v25
	v_cvt_pk_bf16_f32 v42, v10, v26
	v_cvt_pk_bf16_f32 v43, v11, v27
	v_cvt_pk_bf16_f32 v44, v12, v28
	v_cvt_pk_bf16_f32 v45, v13, v29
	v_cvt_pk_bf16_f32 v46, v14, v30
	v_cvt_pk_bf16_f32 v47, v15, v31
	v_cvt_pk_bf16_f32 v48, v16, v32
	v_cvt_pk_bf16_f32 v49, v17, v33
	v_cvt_pk_bf16_f32 v50, v18, v34
	v_cvt_pk_bf16_f32 v51, v19, v35
	global_store_dwordx4 v52, v[36:39], s[74:75]
	global_store_dwordx4 v52, v[40:43], s[74:75] offset:16
	global_store_dwordx4 v52, v[44:47], s[74:75] offset:32
	global_store_dwordx4 v52, v[48:51], s[74:75] offset:48
	s_add_u32 s60, s60, s62
	s_branch .Ltr_a_m0_loop

.Ltr_a_m1_loop:
	s_cmp_ge_u32 s60, s61
	s_cbranch_scc1 .Ltr_a_m1_end
	s_and_b32 s71, s60, 63
	s_lshr_b32 s70, s60, 6
	s_mul_i32 s69, s70, 0x80000
	s_lshl_b32 s80, s71, 7
	s_add_u32 s69, s69, s80
	s_add_u32 s72, s64, s69
	s_addc_u32 s73, s65, 0
	s_mul_i32 s69, s71, 0x8000
	s_lshl_b32 s80, s70, 7
	s_add_u32 s69, s69, s80
	s_add_u32 s74, s66, s69
	s_addc_u32 s75, s67, 0
	v_mov_b32_e32 v3, v2
	global_load_dword v4, v3, s[72:73] nt
	v_add_u32_e32 v3, s68, v3
	global_load_dword v5, v3, s[72:73] nt
	v_add_u32_e32 v3, s68, v3
	global_load_dword v6, v3, s[72:73] nt
	v_add_u32_e32 v3, s68, v3
	global_load_dword v7, v3, s[72:73] nt
	v_add_u32_e32 v3, s68, v3
	global_load_dword v8, v3, s[72:73] nt
	v_add_u32_e32 v3, s68, v3
	global_load_dword v9, v3, s[72:73] nt
	v_add_u32_e32 v3, s68, v3
	global_load_dword v10, v3, s[72:73] nt
	v_add_u32_e32 v3, s68, v3
	global_load_dword v11, v3, s[72:73] nt
	v_add_u32_e32 v3, s68, v3
	global_load_dword v12, v3, s[72:73] nt
	v_add_u32_e32 v3, s68, v3
	global_load_dword v13, v3, s[72:73] nt
	v_add_u32_e32 v3, s68, v3
	global_load_dword v14, v3, s[72:73] nt
	v_add_u32_e32 v3, s68, v3
	global_load_dword v15, v3, s[72:73] nt
	v_add_u32_e32 v3, s68, v3
	global_load_dword v16, v3, s[72:73] nt
	v_add_u32_e32 v3, s68, v3
	global_load_dword v17, v3, s[72:73] nt
	v_add_u32_e32 v3, s68, v3
	global_load_dword v18, v3, s[72:73] nt
	v_add_u32_e32 v3, s68, v3
	global_load_dword v19, v3, s[72:73] nt
	v_add_u32_e32 v3, s68, v3
	global_load_dword v20, v3, s[72:73] nt
	v_add_u32_e32 v3, s68, v3
	global_load_dword v21, v3, s[72:73] nt
	v_add_u32_e32 v3, s68, v3
	global_load_dword v22, v3, s[72:73] nt
	v_add_u32_e32 v3, s68, v3
	global_load_dword v23, v3, s[72:73] nt
	v_add_u32_e32 v3, s68, v3
	global_load_dword v24, v3, s[72:73] nt
	v_add_u32_e32 v3, s68, v3
	global_load_dword v25, v3, s[72:73] nt
	v_add_u32_e32 v3, s68, v3
	global_load_dword v26, v3, s[72:73] nt
	v_add_u32_e32 v3, s68, v3
	global_load_dword v27, v3, s[72:73] nt
	v_add_u32_e32 v3, s68, v3
	global_load_dword v28, v3, s[72:73] nt
	v_add_u32_e32 v3, s68, v3
	global_load_dword v29, v3, s[72:73] nt
	v_add_u32_e32 v3, s68, v3
	global_load_dword v30, v3, s[72:73] nt
	v_add_u32_e32 v3, s68, v3
	global_load_dword v31, v3, s[72:73] nt
	v_add_u32_e32 v3, s68, v3
	global_load_dword v32, v3, s[72:73] nt
	v_add_u32_e32 v3, s68, v3
	global_load_dword v33, v3, s[72:73] nt
	v_add_u32_e32 v3, s68, v3
	global_load_dword v34, v3, s[72:73] nt
	v_add_u32_e32 v3, s68, v3
	global_load_dword v35, v3, s[72:73] nt
	s_waitcnt vmcnt(0)
	v_permlane32_swap_b32_e32 v4, v20
	v_permlane32_swap_b32_e32 v5, v21
	v_permlane32_swap_b32_e32 v6, v22
	v_permlane32_swap_b32_e32 v7, v23
	v_permlane32_swap_b32_e32 v8, v24
	v_permlane32_swap_b32_e32 v9, v25
	v_permlane32_swap_b32_e32 v10, v26
	v_permlane32_swap_b32_e32 v11, v27
	v_permlane32_swap_b32_e32 v12, v28
	v_permlane32_swap_b32_e32 v13, v29
	v_permlane32_swap_b32_e32 v14, v30
	v_permlane32_swap_b32_e32 v15, v31
	v_permlane32_swap_b32_e32 v16, v32
	v_permlane32_swap_b32_e32 v17, v33
	v_permlane32_swap_b32_e32 v18, v34
	v_permlane32_swap_b32_e32 v19, v35
	v_cvt_pk_bf16_f32 v36, v4, v20
	v_cvt_pk_bf16_f32 v37, v5, v21
	v_cvt_pk_bf16_f32 v38, v6, v22
	v_cvt_pk_bf16_f32 v39, v7, v23
	v_cvt_pk_bf16_f32 v40, v8, v24
	v_cvt_pk_bf16_f32 v41, v9, v25
	v_cvt_pk_bf16_f32 v42, v10, v26
	v_cvt_pk_bf16_f32 v43, v11, v27
	v_cvt_pk_bf16_f32 v44, v12, v28
	v_cvt_pk_bf16_f32 v45, v13, v29
	v_cvt_pk_bf16_f32 v46, v14, v30
	v_cvt_pk_bf16_f32 v47, v15, v31
	v_cvt_pk_bf16_f32 v48, v16, v32
	v_cvt_pk_bf16_f32 v49, v17, v33
	v_cvt_pk_bf16_f32 v50, v18, v34
	v_cvt_pk_bf16_f32 v51, v19, v35
	global_store_dwordx4 v52, v[36:39], s[74:75]
	global_store_dwordx4 v52, v[40:43], s[74:75] offset:16
	global_store_dwordx4 v52, v[44:47], s[74:75] offset:32
	global_store_dwordx4 v52, v[48:51], s[74:75] offset:48
	s_add_u32 s60, s60, s62
	s_branch .Ltr_a_m1_loop

.Ltr_a_m2_loop:
	s_cmp_ge_u32 s60, s61
	s_cbranch_scc1 .Ltr_a_m2_end
	s_and_b32 s71, s60, 63
	s_lshr_b32 s70, s60, 6
	s_mul_i32 s69, s70, 0x80000
	s_lshl_b32 s80, s71, 7
	s_add_u32 s69, s69, s80
	s_add_u32 s72, s64, s69
	s_addc_u32 s73, s65, 0
	s_mul_i32 s69, s71, 0x20000
	s_lshl_b32 s80, s70, 7
	s_add_u32 s69, s69, s80
	s_add_u32 s74, s66, s69
	s_addc_u32 s75, s67, 0
	v_mov_b32_e32 v3, v2
	global_load_dword v4, v3, s[72:73] nt
	v_add_u32_e32 v3, s68, v3
	global_load_dword v5, v3, s[72:73] nt
	v_add_u32_e32 v3, s68, v3
	global_load_dword v6, v3, s[72:73] nt
	v_add_u32_e32 v3, s68, v3
	global_load_dword v7, v3, s[72:73] nt
	v_add_u32_e32 v3, s68, v3
	global_load_dword v8, v3, s[72:73] nt
	v_add_u32_e32 v3, s68, v3
	global_load_dword v9, v3, s[72:73] nt
	v_add_u32_e32 v3, s68, v3
	global_load_dword v10, v3, s[72:73] nt
	v_add_u32_e32 v3, s68, v3
	global_load_dword v11, v3, s[72:73] nt
	v_add_u32_e32 v3, s68, v3
	global_load_dword v12, v3, s[72:73] nt
	v_add_u32_e32 v3, s68, v3
	global_load_dword v13, v3, s[72:73] nt
	v_add_u32_e32 v3, s68, v3
	global_load_dword v14, v3, s[72:73] nt
	v_add_u32_e32 v3, s68, v3
	global_load_dword v15, v3, s[72:73] nt
	v_add_u32_e32 v3, s68, v3
	global_load_dword v16, v3, s[72:73] nt
	v_add_u32_e32 v3, s68, v3
	global_load_dword v17, v3, s[72:73] nt
	v_add_u32_e32 v3, s68, v3
	global_load_dword v18, v3, s[72:73] nt
	v_add_u32_e32 v3, s68, v3
	global_load_dword v19, v3, s[72:73] nt
	v_add_u32_e32 v3, s68, v3
	global_load_dword v20, v3, s[72:73] nt
	v_add_u32_e32 v3, s68, v3
	global_load_dword v21, v3, s[72:73] nt
	v_add_u32_e32 v3, s68, v3
	global_load_dword v22, v3, s[72:73] nt
	v_add_u32_e32 v3, s68, v3
	global_load_dword v23, v3, s[72:73] nt
	v_add_u32_e32 v3, s68, v3
	global_load_dword v24, v3, s[72:73] nt
	v_add_u32_e32 v3, s68, v3
	global_load_dword v25, v3, s[72:73] nt
	v_add_u32_e32 v3, s68, v3
	global_load_dword v26, v3, s[72:73] nt
	v_add_u32_e32 v3, s68, v3
	global_load_dword v27, v3, s[72:73] nt
	v_add_u32_e32 v3, s68, v3
	global_load_dword v28, v3, s[72:73] nt
	v_add_u32_e32 v3, s68, v3
	global_load_dword v29, v3, s[72:73] nt
	v_add_u32_e32 v3, s68, v3
	global_load_dword v30, v3, s[72:73] nt
	v_add_u32_e32 v3, s68, v3
	global_load_dword v31, v3, s[72:73] nt
	v_add_u32_e32 v3, s68, v3
	global_load_dword v32, v3, s[72:73] nt
	v_add_u32_e32 v3, s68, v3
	global_load_dword v33, v3, s[72:73] nt
	v_add_u32_e32 v3, s68, v3
	global_load_dword v34, v3, s[72:73] nt
	v_add_u32_e32 v3, s68, v3
	global_load_dword v35, v3, s[72:73] nt
	s_waitcnt vmcnt(0)
	v_permlane32_swap_b32_e32 v4, v20
	v_permlane32_swap_b32_e32 v5, v21
	v_permlane32_swap_b32_e32 v6, v22
	v_permlane32_swap_b32_e32 v7, v23
	v_permlane32_swap_b32_e32 v8, v24
	v_permlane32_swap_b32_e32 v9, v25
	v_permlane32_swap_b32_e32 v10, v26
	v_permlane32_swap_b32_e32 v11, v27
	v_permlane32_swap_b32_e32 v12, v28
	v_permlane32_swap_b32_e32 v13, v29
	v_permlane32_swap_b32_e32 v14, v30
	v_permlane32_swap_b32_e32 v15, v31
	v_permlane32_swap_b32_e32 v16, v32
	v_permlane32_swap_b32_e32 v17, v33
	v_permlane32_swap_b32_e32 v18, v34
	v_permlane32_swap_b32_e32 v19, v35
	v_cvt_pk_bf16_f32 v36, v4, v20
	v_cvt_pk_bf16_f32 v37, v5, v21
	v_cvt_pk_bf16_f32 v38, v6, v22
	v_cvt_pk_bf16_f32 v39, v7, v23
	v_cvt_pk_bf16_f32 v40, v8, v24
	v_cvt_pk_bf16_f32 v41, v9, v25
	v_cvt_pk_bf16_f32 v42, v10, v26
	v_cvt_pk_bf16_f32 v43, v11, v27
	v_cvt_pk_bf16_f32 v44, v12, v28
	v_cvt_pk_bf16_f32 v45, v13, v29
	v_cvt_pk_bf16_f32 v46, v14, v30
	v_cvt_pk_bf16_f32 v47, v15, v31
	v_cvt_pk_bf16_f32 v48, v16, v32
	v_cvt_pk_bf16_f32 v49, v17, v33
	v_cvt_pk_bf16_f32 v50, v18, v34
	v_cvt_pk_bf16_f32 v51, v19, v35
	global_store_dwordx4 v52, v[36:39], s[74:75]
	global_store_dwordx4 v52, v[40:43], s[74:75] offset:16
	global_store_dwordx4 v52, v[44:47], s[74:75] offset:32
	global_store_dwordx4 v52, v[48:51], s[74:75] offset:48
	s_add_u32 s60, s60, s62
	s_branch .Ltr_a_m2_loop

.Ltr_a_m3_loop:
	s_cmp_ge_u32 s60, s61
	s_cbranch_scc1 .Ltr_a_m3_end
	s_and_b32 s71, s60, 255
	s_lshr_b32 s70, s60, 8
	s_mul_i32 s69, s70, 0x200000
	s_lshl_b32 s80, s71, 7
	s_add_u32 s69, s69, s80
	s_add_u32 s72, s64, s69
	s_addc_u32 s73, s65, 0
	s_mul_i32 s69, s71, 0x20000
	s_lshl_b32 s80, s70, 7
	s_add_u32 s69, s69, s80
	s_add_u32 s74, s66, s69
	s_addc_u32 s75, s67, 0
	v_mov_b32_e32 v3, v2
	global_load_dword v4, v3, s[72:73] nt
	v_add_u32_e32 v3, s68, v3
	global_load_dword v5, v3, s[72:73] nt
	v_add_u32_e32 v3, s68, v3
	global_load_dword v6, v3, s[72:73] nt
	v_add_u32_e32 v3, s68, v3
	global_load_dword v7, v3, s[72:73] nt
	v_add_u32_e32 v3, s68, v3
	global_load_dword v8, v3, s[72:73] nt
	v_add_u32_e32 v3, s68, v3
	global_load_dword v9, v3, s[72:73] nt
	v_add_u32_e32 v3, s68, v3
	global_load_dword v10, v3, s[72:73] nt
	v_add_u32_e32 v3, s68, v3
	global_load_dword v11, v3, s[72:73] nt
	v_add_u32_e32 v3, s68, v3
	global_load_dword v12, v3, s[72:73] nt
	v_add_u32_e32 v3, s68, v3
	global_load_dword v13, v3, s[72:73] nt
	v_add_u32_e32 v3, s68, v3
	global_load_dword v14, v3, s[72:73] nt
	v_add_u32_e32 v3, s68, v3
	global_load_dword v15, v3, s[72:73] nt
	v_add_u32_e32 v3, s68, v3
	global_load_dword v16, v3, s[72:73] nt
	v_add_u32_e32 v3, s68, v3
	global_load_dword v17, v3, s[72:73] nt
	v_add_u32_e32 v3, s68, v3
	global_load_dword v18, v3, s[72:73] nt
	v_add_u32_e32 v3, s68, v3
	global_load_dword v19, v3, s[72:73] nt
	v_add_u32_e32 v3, s68, v3
	global_load_dword v20, v3, s[72:73] nt
	v_add_u32_e32 v3, s68, v3
	global_load_dword v21, v3, s[72:73] nt
	v_add_u32_e32 v3, s68, v3
	global_load_dword v22, v3, s[72:73] nt
	v_add_u32_e32 v3, s68, v3
	global_load_dword v23, v3, s[72:73] nt
	v_add_u32_e32 v3, s68, v3
	global_load_dword v24, v3, s[72:73] nt
	v_add_u32_e32 v3, s68, v3
	global_load_dword v25, v3, s[72:73] nt
	v_add_u32_e32 v3, s68, v3
	global_load_dword v26, v3, s[72:73] nt
	v_add_u32_e32 v3, s68, v3
	global_load_dword v27, v3, s[72:73] nt
	v_add_u32_e32 v3, s68, v3
	global_load_dword v28, v3, s[72:73] nt
	v_add_u32_e32 v3, s68, v3
	global_load_dword v29, v3, s[72:73] nt
	v_add_u32_e32 v3, s68, v3
	global_load_dword v30, v3, s[72:73] nt
	v_add_u32_e32 v3, s68, v3
	global_load_dword v31, v3, s[72:73] nt
	v_add_u32_e32 v3, s68, v3
	global_load_dword v32, v3, s[72:73] nt
	v_add_u32_e32 v3, s68, v3
	global_load_dword v33, v3, s[72:73] nt
	v_add_u32_e32 v3, s68, v3
	global_load_dword v34, v3, s[72:73] nt
	v_add_u32_e32 v3, s68, v3
	global_load_dword v35, v3, s[72:73] nt
	s_waitcnt vmcnt(0)
	v_permlane32_swap_b32_e32 v4, v20
	v_permlane32_swap_b32_e32 v5, v21
	v_permlane32_swap_b32_e32 v6, v22
	v_permlane32_swap_b32_e32 v7, v23
	v_permlane32_swap_b32_e32 v8, v24
	v_permlane32_swap_b32_e32 v9, v25
	v_permlane32_swap_b32_e32 v10, v26
	v_permlane32_swap_b32_e32 v11, v27
	v_permlane32_swap_b32_e32 v12, v28
	v_permlane32_swap_b32_e32 v13, v29
	v_permlane32_swap_b32_e32 v14, v30
	v_permlane32_swap_b32_e32 v15, v31
	v_permlane32_swap_b32_e32 v16, v32
	v_permlane32_swap_b32_e32 v17, v33
	v_permlane32_swap_b32_e32 v18, v34
	v_permlane32_swap_b32_e32 v19, v35
	v_cvt_pk_bf16_f32 v36, v4, v20
	v_cvt_pk_bf16_f32 v37, v5, v21
	v_cvt_pk_bf16_f32 v38, v6, v22
	v_cvt_pk_bf16_f32 v39, v7, v23
	v_cvt_pk_bf16_f32 v40, v8, v24
	v_cvt_pk_bf16_f32 v41, v9, v25
	v_cvt_pk_bf16_f32 v42, v10, v26
	v_cvt_pk_bf16_f32 v43, v11, v27
	v_cvt_pk_bf16_f32 v44, v12, v28
	v_cvt_pk_bf16_f32 v45, v13, v29
	v_cvt_pk_bf16_f32 v46, v14, v30
	v_cvt_pk_bf16_f32 v47, v15, v31
	v_cvt_pk_bf16_f32 v48, v16, v32
	v_cvt_pk_bf16_f32 v49, v17, v33
	v_cvt_pk_bf16_f32 v50, v18, v34
	v_cvt_pk_bf16_f32 v51, v19, v35
	global_store_dwordx4 v52, v[36:39], s[74:75]
	global_store_dwordx4 v52, v[40:43], s[74:75] offset:16
	global_store_dwordx4 v52, v[44:47], s[74:75] offset:32
	global_store_dwordx4 v52, v[48:51], s[74:75] offset:48
	s_add_u32 s60, s60, s62
	s_branch .Ltr_a_m3_loop

.Ltr_a_m4_loop:
	s_cmp_ge_u32 s60, s61
	s_cbranch_scc1 .Ltr_a_m4_end
	s_and_b32 s71, s60, 63
	s_lshr_b32 s70, s60, 6
	s_mul_i32 s69, s70, 0x80000
	s_lshl_b32 s80, s71, 7
	s_add_u32 s69, s69, s80
	s_add_u32 s72, s64, s69
	s_addc_u32 s73, s65, 0
	s_mul_i32 s69, s71, 0x80000
	s_lshl_b32 s80, s70, 7
	s_add_u32 s69, s69, s80
	s_add_u32 s74, s66, s69
	s_addc_u32 s75, s67, 0
	v_mov_b32_e32 v3, v2
	global_load_dword v4, v3, s[72:73] nt
	v_add_u32_e32 v3, s68, v3
	global_load_dword v5, v3, s[72:73] nt
	v_add_u32_e32 v3, s68, v3
	global_load_dword v6, v3, s[72:73] nt
	v_add_u32_e32 v3, s68, v3
	global_load_dword v7, v3, s[72:73] nt
	v_add_u32_e32 v3, s68, v3
	global_load_dword v8, v3, s[72:73] nt
	v_add_u32_e32 v3, s68, v3
	global_load_dword v9, v3, s[72:73] nt
	v_add_u32_e32 v3, s68, v3
	global_load_dword v10, v3, s[72:73] nt
	v_add_u32_e32 v3, s68, v3
	global_load_dword v11, v3, s[72:73] nt
	v_add_u32_e32 v3, s68, v3
	global_load_dword v12, v3, s[72:73] nt
	v_add_u32_e32 v3, s68, v3
	global_load_dword v13, v3, s[72:73] nt
	v_add_u32_e32 v3, s68, v3
	global_load_dword v14, v3, s[72:73] nt
	v_add_u32_e32 v3, s68, v3
	global_load_dword v15, v3, s[72:73] nt
	v_add_u32_e32 v3, s68, v3
	global_load_dword v16, v3, s[72:73] nt
	v_add_u32_e32 v3, s68, v3
	global_load_dword v17, v3, s[72:73] nt
	v_add_u32_e32 v3, s68, v3
	global_load_dword v18, v3, s[72:73] nt
	v_add_u32_e32 v3, s68, v3
	global_load_dword v19, v3, s[72:73] nt
	v_add_u32_e32 v3, s68, v3
	global_load_dword v20, v3, s[72:73] nt
	v_add_u32_e32 v3, s68, v3
	global_load_dword v21, v3, s[72:73] nt
	v_add_u32_e32 v3, s68, v3
	global_load_dword v22, v3, s[72:73] nt
	v_add_u32_e32 v3, s68, v3
	global_load_dword v23, v3, s[72:73] nt
	v_add_u32_e32 v3, s68, v3
	global_load_dword v24, v3, s[72:73] nt
	v_add_u32_e32 v3, s68, v3
	global_load_dword v25, v3, s[72:73] nt
	v_add_u32_e32 v3, s68, v3
	global_load_dword v26, v3, s[72:73] nt
	v_add_u32_e32 v3, s68, v3
	global_load_dword v27, v3, s[72:73] nt
	v_add_u32_e32 v3, s68, v3
	global_load_dword v28, v3, s[72:73] nt
	v_add_u32_e32 v3, s68, v3
	global_load_dword v29, v3, s[72:73] nt
	v_add_u32_e32 v3, s68, v3
	global_load_dword v30, v3, s[72:73] nt
	v_add_u32_e32 v3, s68, v3
	global_load_dword v31, v3, s[72:73] nt
	v_add_u32_e32 v3, s68, v3
	global_load_dword v32, v3, s[72:73] nt
	v_add_u32_e32 v3, s68, v3
	global_load_dword v33, v3, s[72:73] nt
	v_add_u32_e32 v3, s68, v3
	global_load_dword v34, v3, s[72:73] nt
	v_add_u32_e32 v3, s68, v3
	global_load_dword v35, v3, s[72:73] nt
	s_waitcnt vmcnt(0)
	v_permlane32_swap_b32_e32 v4, v20
	v_permlane32_swap_b32_e32 v5, v21
	v_permlane32_swap_b32_e32 v6, v22
	v_permlane32_swap_b32_e32 v7, v23
	v_permlane32_swap_b32_e32 v8, v24
	v_permlane32_swap_b32_e32 v9, v25
	v_permlane32_swap_b32_e32 v10, v26
	v_permlane32_swap_b32_e32 v11, v27
	v_permlane32_swap_b32_e32 v12, v28
	v_permlane32_swap_b32_e32 v13, v29
	v_permlane32_swap_b32_e32 v14, v30
	v_permlane32_swap_b32_e32 v15, v31
	v_permlane32_swap_b32_e32 v16, v32
	v_permlane32_swap_b32_e32 v17, v33
	v_permlane32_swap_b32_e32 v18, v34
	v_permlane32_swap_b32_e32 v19, v35
	v_cvt_pk_bf16_f32 v36, v4, v20
	v_cvt_pk_bf16_f32 v37, v5, v21
	v_cvt_pk_bf16_f32 v38, v6, v22
	v_cvt_pk_bf16_f32 v39, v7, v23
	v_cvt_pk_bf16_f32 v40, v8, v24
	v_cvt_pk_bf16_f32 v41, v9, v25
	v_cvt_pk_bf16_f32 v42, v10, v26
	v_cvt_pk_bf16_f32 v43, v11, v27
	v_cvt_pk_bf16_f32 v44, v12, v28
	v_cvt_pk_bf16_f32 v45, v13, v29
	v_cvt_pk_bf16_f32 v46, v14, v30
	v_cvt_pk_bf16_f32 v47, v15, v31
	v_cvt_pk_bf16_f32 v48, v16, v32
	v_cvt_pk_bf16_f32 v49, v17, v33
	v_cvt_pk_bf16_f32 v50, v18, v34
	v_cvt_pk_bf16_f32 v51, v19, v35
	global_store_dwordx4 v52, v[36:39], s[74:75]
	global_store_dwordx4 v52, v[40:43], s[74:75] offset:16
	global_store_dwordx4 v52, v[44:47], s[74:75] offset:32
	global_store_dwordx4 v52, v[48:51], s[74:75] offset:48
	s_add_u32 s60, s60, s62
	s_branch .Ltr_a_m4_loop

.Ltr_b_m0_loop:
	s_cmp_ge_u32 s60, s61
	s_cbranch_scc1 .Ltr_b_m0_end
	s_mul_i32 s70, s60, 2913
	s_lshr_b32 s70, s70, 18
	s_mul_i32 s69, s70, 90
	s_sub_u32 s71, s60, s69
	s_mul_i32 s69, s70, 0xb4000
	s_lshl_b32 s80, s71, 7
	s_add_u32 s69, s69, s80
	s_add_u32 s72, s64, s69
	s_addc_u32 s73, s65, 0
	s_mul_i32 s69, s71, 0x20000
	s_lshl_b32 s80, s70, 7
	s_add_u32 s69, s69, s80
	s_add_u32 s74, s66, s69
	s_addc_u32 s75, s67, 0
	v_mov_b32_e32 v3, v2
	global_load_dword v4, v3, s[72:73] nt
	v_add_u32_e32 v3, s68, v3
	global_load_dword v5, v3, s[72:73] nt
	v_add_u32_e32 v3, s68, v3
	global_load_dword v6, v3, s[72:73] nt
	v_add_u32_e32 v3, s68, v3
	global_load_dword v7, v3, s[72:73] nt
	v_add_u32_e32 v3, s68, v3
	global_load_dword v8, v3, s[72:73] nt
	v_add_u32_e32 v3, s68, v3
	global_load_dword v9, v3, s[72:73] nt
	v_add_u32_e32 v3, s68, v3
	global_load_dword v10, v3, s[72:73] nt
	v_add_u32_e32 v3, s68, v3
	global_load_dword v11, v3, s[72:73] nt
	v_add_u32_e32 v3, s68, v3
	global_load_dword v12, v3, s[72:73] nt
	v_add_u32_e32 v3, s68, v3
	global_load_dword v13, v3, s[72:73] nt
	v_add_u32_e32 v3, s68, v3
	global_load_dword v14, v3, s[72:73] nt
	v_add_u32_e32 v3, s68, v3
	global_load_dword v15, v3, s[72:73] nt
	v_add_u32_e32 v3, s68, v3
	global_load_dword v16, v3, s[72:73] nt
	v_add_u32_e32 v3, s68, v3
	global_load_dword v17, v3, s[72:73] nt
	v_add_u32_e32 v3, s68, v3
	global_load_dword v18, v3, s[72:73] nt
	v_add_u32_e32 v3, s68, v3
	global_load_dword v19, v3, s[72:73] nt
	v_add_u32_e32 v3, s68, v3
	global_load_dword v20, v3, s[72:73] nt
	v_add_u32_e32 v3, s68, v3
	global_load_dword v21, v3, s[72:73] nt
	v_add_u32_e32 v3, s68, v3
	global_load_dword v22, v3, s[72:73] nt
	v_add_u32_e32 v3, s68, v3
	global_load_dword v23, v3, s[72:73] nt
	v_add_u32_e32 v3, s68, v3
	global_load_dword v24, v3, s[72:73] nt
	v_add_u32_e32 v3, s68, v3
	global_load_dword v25, v3, s[72:73] nt
	v_add_u32_e32 v3, s68, v3
	global_load_dword v26, v3, s[72:73] nt
	v_add_u32_e32 v3, s68, v3
	global_load_dword v27, v3, s[72:73] nt
	v_add_u32_e32 v3, s68, v3
	global_load_dword v28, v3, s[72:73] nt
	v_add_u32_e32 v3, s68, v3
	global_load_dword v29, v3, s[72:73] nt
	v_add_u32_e32 v3, s68, v3
	global_load_dword v30, v3, s[72:73] nt
	v_add_u32_e32 v3, s68, v3
	global_load_dword v31, v3, s[72:73] nt
	v_add_u32_e32 v3, s68, v3
	global_load_dword v32, v3, s[72:73] nt
	v_add_u32_e32 v3, s68, v3
	global_load_dword v33, v3, s[72:73] nt
	v_add_u32_e32 v3, s68, v3
	global_load_dword v34, v3, s[72:73] nt
	v_add_u32_e32 v3, s68, v3
	global_load_dword v35, v3, s[72:73] nt
	s_waitcnt vmcnt(0)
	v_permlane32_swap_b32_e32 v4, v20
	v_permlane32_swap_b32_e32 v5, v21
	v_permlane32_swap_b32_e32 v6, v22
	v_permlane32_swap_b32_e32 v7, v23
	v_permlane32_swap_b32_e32 v8, v24
	v_permlane32_swap_b32_e32 v9, v25
	v_permlane32_swap_b32_e32 v10, v26
	v_permlane32_swap_b32_e32 v11, v27
	v_permlane32_swap_b32_e32 v12, v28
	v_permlane32_swap_b32_e32 v13, v29
	v_permlane32_swap_b32_e32 v14, v30
	v_permlane32_swap_b32_e32 v15, v31
	v_permlane32_swap_b32_e32 v16, v32
	v_permlane32_swap_b32_e32 v17, v33
	v_permlane32_swap_b32_e32 v18, v34
	v_permlane32_swap_b32_e32 v19, v35
	v_cvt_pk_bf16_f32 v36, v4, v20
	v_cvt_pk_bf16_f32 v37, v5, v21
	v_cvt_pk_bf16_f32 v38, v6, v22
	v_cvt_pk_bf16_f32 v39, v7, v23
	v_cvt_pk_bf16_f32 v40, v8, v24
	v_cvt_pk_bf16_f32 v41, v9, v25
	v_cvt_pk_bf16_f32 v42, v10, v26
	v_cvt_pk_bf16_f32 v43, v11, v27
	v_cvt_pk_bf16_f32 v44, v12, v28
	v_cvt_pk_bf16_f32 v45, v13, v29
	v_cvt_pk_bf16_f32 v46, v14, v30
	v_cvt_pk_bf16_f32 v47, v15, v31
	v_cvt_pk_bf16_f32 v48, v16, v32
	v_cvt_pk_bf16_f32 v49, v17, v33
	v_cvt_pk_bf16_f32 v50, v18, v34
	v_cvt_pk_bf16_f32 v51, v19, v35
	global_store_dwordx4 v52, v[36:39], s[74:75]
	global_store_dwordx4 v52, v[40:43], s[74:75] offset:16
	global_store_dwordx4 v52, v[44:47], s[74:75] offset:32
	global_store_dwordx4 v52, v[48:51], s[74:75] offset:48
	s_add_u32 s60, s60, s62
	s_branch .Ltr_b_m0_loop

.Lnm_fin_loop:
	s_add_i32 s8, s4, -15
	s_ashr_i32 s9, s8, 31
	s_lshl_b64 s[10:11], s[8:9], 13
	s_mov_b64 s[24:25], s[10:11]
	v_lshl_add_u64 v[124:125], v[68:69], 0, s[10:11]
	global_load_dwordx4 v[4:7], v[124:125], off nt
	s_add_u32 s10, s10, 0x2000
	s_addc_u32 s11, s11, 0
	v_lshl_add_u64 v[124:125], v[68:69], 0, s[10:11]
	global_load_dwordx4 v[8:11], v[124:125], off nt
	s_add_u32 s10, s10, 0x2000
	s_addc_u32 s11, s11, 0
	v_lshl_add_u64 v[124:125], v[68:69], 0, s[10:11]
	global_load_dwordx4 v[12:15], v[124:125], off nt
	s_add_u32 s10, s10, 0x2000
	s_addc_u32 s11, s11, 0
	v_lshl_add_u64 v[124:125], v[68:69], 0, s[10:11]
	global_load_dwordx4 v[16:19], v[124:125], off nt
	s_add_u32 s10, s10, 0x2000
	s_addc_u32 s11, s11, 0
	v_lshl_add_u64 v[124:125], v[68:69], 0, s[10:11]
	global_load_dwordx4 v[20:23], v[124:125], off nt
	s_add_u32 s10, s10, 0x2000
	s_addc_u32 s11, s11, 0
	v_lshl_add_u64 v[124:125], v[68:69], 0, s[10:11]
	global_load_dwordx4 v[24:27], v[124:125], off nt
	s_add_u32 s10, s10, 0x2000
	s_addc_u32 s11, s11, 0
	v_lshl_add_u64 v[124:125], v[68:69], 0, s[10:11]
	global_load_dwordx4 v[28:31], v[124:125], off nt
	s_add_u32 s10, s10, 0x2000
	s_addc_u32 s11, s11, 0
	v_lshl_add_u64 v[124:125], v[68:69], 0, s[10:11]
	global_load_dwordx4 v[32:35], v[124:125], off nt
	s_add_u32 s10, s10, 0x2000
	s_addc_u32 s11, s11, 0
	v_lshl_add_u64 v[124:125], v[68:69], 0, s[10:11]
	global_load_dwordx4 v[36:39], v[124:125], off nt
	s_add_u32 s10, s10, 0x2000
	s_addc_u32 s11, s11, 0
	v_lshl_add_u64 v[124:125], v[68:69], 0, s[10:11]
	global_load_dwordx4 v[40:43], v[124:125], off nt
	s_add_u32 s10, s10, 0x2000
	s_addc_u32 s11, s11, 0
	v_lshl_add_u64 v[124:125], v[68:69], 0, s[10:11]
	global_load_dwordx4 v[44:47], v[124:125], off nt
	s_add_u32 s10, s10, 0x2000
	s_addc_u32 s11, s11, 0
	v_lshl_add_u64 v[124:125], v[68:69], 0, s[10:11]
	global_load_dwordx4 v[48:51], v[124:125], off nt
	s_add_u32 s10, s10, 0x2000
	s_addc_u32 s11, s11, 0
	v_lshl_add_u64 v[124:125], v[68:69], 0, s[10:11]
	global_load_dwordx4 v[52:55], v[124:125], off nt
	s_add_u32 s10, s10, 0x2000
	s_addc_u32 s11, s11, 0
	v_lshl_add_u64 v[124:125], v[68:69], 0, s[10:11]
	global_load_dwordx4 v[56:59], v[124:125], off nt
	s_add_u32 s10, s10, 0x2000
	s_addc_u32 s11, s11, 0
	v_lshl_add_u64 v[124:125], v[68:69], 0, s[10:11]
	global_load_dwordx4 v[60:63], v[124:125], off nt
	s_add_u32 s10, s10, 0x2000
	s_addc_u32 s11, s11, 0
	v_lshl_add_u64 v[124:125], v[68:69], 0, s[10:11]
	global_load_dwordx4 v[64:67], v[124:125], off nt
	s_waitcnt vmcnt(15)
	v_mul_f32_e32 v84, v5, v5
	v_mul_f32_e32 v100, v7, v7
	v_fmac_f32_e32 v84, v4, v4
	v_fmac_f32_e32 v100, v6, v6
	v_add_f32_e32 v84, v84, v100
	s_waitcnt vmcnt(14)
	v_mul_f32_e32 v85, v9, v9
	v_mul_f32_e32 v101, v11, v11
	v_fmac_f32_e32 v85, v8, v8
	v_fmac_f32_e32 v101, v10, v10
	v_add_f32_e32 v85, v85, v101
	s_waitcnt vmcnt(13)
	v_mul_f32_e32 v86, v13, v13
	v_mul_f32_e32 v102, v15, v15
	v_fmac_f32_e32 v86, v12, v12
	v_fmac_f32_e32 v102, v14, v14
	v_add_f32_e32 v86, v86, v102
	s_waitcnt vmcnt(12)
	v_mul_f32_e32 v87, v17, v17
	v_mul_f32_e32 v103, v19, v19
	v_fmac_f32_e32 v87, v16, v16
	v_fmac_f32_e32 v103, v18, v18
	v_add_f32_e32 v87, v87, v103
	s_waitcnt vmcnt(11)
	v_mul_f32_e32 v88, v21, v21
	v_mul_f32_e32 v104, v23, v23
	v_fmac_f32_e32 v88, v20, v20
	v_fmac_f32_e32 v104, v22, v22
	v_add_f32_e32 v88, v88, v104
	s_waitcnt vmcnt(10)
	v_mul_f32_e32 v89, v25, v25
	v_mul_f32_e32 v105, v27, v27
	v_fmac_f32_e32 v89, v24, v24
	v_fmac_f32_e32 v105, v26, v26
	v_add_f32_e32 v89, v89, v105
	s_waitcnt vmcnt(9)
	v_mul_f32_e32 v90, v29, v29
	v_mul_f32_e32 v106, v31, v31
	v_fmac_f32_e32 v90, v28, v28
	v_fmac_f32_e32 v106, v30, v30
	v_add_f32_e32 v90, v90, v106
	s_waitcnt vmcnt(8)
	v_mul_f32_e32 v91, v33, v33
	v_mul_f32_e32 v107, v35, v35
	v_fmac_f32_e32 v91, v32, v32
	v_fmac_f32_e32 v107, v34, v34
	v_add_f32_e32 v91, v91, v107
	s_waitcnt vmcnt(7)
	v_mul_f32_e32 v92, v37, v37
	v_mul_f32_e32 v108, v39, v39
	v_fmac_f32_e32 v92, v36, v36
	v_fmac_f32_e32 v108, v38, v38
	v_add_f32_e32 v92, v92, v108
	s_waitcnt vmcnt(6)
	v_mul_f32_e32 v93, v41, v41
	v_mul_f32_e32 v109, v43, v43
	v_fmac_f32_e32 v93, v40, v40
	v_fmac_f32_e32 v109, v42, v42
	v_add_f32_e32 v93, v93, v109
	s_waitcnt vmcnt(5)
	v_mul_f32_e32 v94, v45, v45
	v_mul_f32_e32 v110, v47, v47
	v_fmac_f32_e32 v94, v44, v44
	v_fmac_f32_e32 v110, v46, v46
	v_add_f32_e32 v94, v94, v110
	s_waitcnt vmcnt(4)
	v_mul_f32_e32 v95, v49, v49
	v_mul_f32_e32 v111, v51, v51
	v_fmac_f32_e32 v95, v48, v48
	v_fmac_f32_e32 v111, v50, v50
	v_add_f32_e32 v95, v95, v111
	s_waitcnt vmcnt(3)
	v_mul_f32_e32 v96, v53, v53
	v_mul_f32_e32 v112, v55, v55
	v_fmac_f32_e32 v96, v52, v52
	v_fmac_f32_e32 v112, v54, v54
	v_add_f32_e32 v96, v96, v112
	s_waitcnt vmcnt(2)
	v_mul_f32_e32 v97, v57, v57
	v_mul_f32_e32 v113, v59, v59
	v_fmac_f32_e32 v97, v56, v56
	v_fmac_f32_e32 v113, v58, v58
	v_add_f32_e32 v97, v97, v113
	s_waitcnt vmcnt(1)
	v_mul_f32_e32 v98, v61, v61
	v_mul_f32_e32 v114, v63, v63
	v_fmac_f32_e32 v98, v60, v60
	v_fmac_f32_e32 v114, v62, v62
	v_add_f32_e32 v98, v98, v114
	s_waitcnt vmcnt(0)
	v_mul_f32_e32 v99, v65, v65
	v_mul_f32_e32 v115, v67, v67
	v_fmac_f32_e32 v99, v64, v64
	v_fmac_f32_e32 v115, v66, v66
	v_add_f32_e32 v99, v99, v115
	ds_bpermute_b32 v100, v73, v84
	ds_bpermute_b32 v101, v73, v85
	ds_bpermute_b32 v102, v73, v86
	ds_bpermute_b32 v103, v73, v87
	ds_bpermute_b32 v104, v73, v88
	ds_bpermute_b32 v105, v73, v89
	ds_bpermute_b32 v106, v73, v90
	ds_bpermute_b32 v107, v73, v91
	ds_bpermute_b32 v108, v73, v92
	ds_bpermute_b32 v109, v73, v93
	ds_bpermute_b32 v110, v73, v94
	ds_bpermute_b32 v111, v73, v95
	ds_bpermute_b32 v112, v73, v96
	ds_bpermute_b32 v113, v73, v97
	ds_bpermute_b32 v114, v73, v98
	ds_bpermute_b32 v115, v73, v99
	s_waitcnt lgkmcnt(15)
	v_add_f32_e32 v84, v84, v100
	s_waitcnt lgkmcnt(14)
	v_add_f32_e32 v85, v85, v101
	s_waitcnt lgkmcnt(13)
	v_add_f32_e32 v86, v86, v102
	s_waitcnt lgkmcnt(12)
	v_add_f32_e32 v87, v87, v103
	s_waitcnt lgkmcnt(11)
	v_add_f32_e32 v88, v88, v104
	s_waitcnt lgkmcnt(10)
	v_add_f32_e32 v89, v89, v105
	s_waitcnt lgkmcnt(9)
	v_add_f32_e32 v90, v90, v106
	s_waitcnt lgkmcnt(8)
	v_add_f32_e32 v91, v91, v107
	s_waitcnt lgkmcnt(7)
	v_add_f32_e32 v92, v92, v108
	s_waitcnt lgkmcnt(6)
	v_add_f32_e32 v93, v93, v109
	s_waitcnt lgkmcnt(5)
	v_add_f32_e32 v94, v94, v110
	s_waitcnt lgkmcnt(4)
	v_add_f32_e32 v95, v95, v111
	s_waitcnt lgkmcnt(3)
	v_add_f32_e32 v96, v96, v112
	s_waitcnt lgkmcnt(2)
	v_add_f32_e32 v97, v97, v113
	s_waitcnt lgkmcnt(1)
	v_add_f32_e32 v98, v98, v114
	s_waitcnt lgkmcnt(0)
	v_add_f32_e32 v99, v99, v115
	ds_bpermute_b32 v100, v74, v84
	ds_bpermute_b32 v101, v74, v85
	ds_bpermute_b32 v102, v74, v86
	ds_bpermute_b32 v103, v74, v87
	ds_bpermute_b32 v104, v74, v88
	ds_bpermute_b32 v105, v74, v89
	ds_bpermute_b32 v106, v74, v90
	ds_bpermute_b32 v107, v74, v91
	ds_bpermute_b32 v108, v74, v92
	ds_bpermute_b32 v109, v74, v93
	ds_bpermute_b32 v110, v74, v94
	ds_bpermute_b32 v111, v74, v95
	ds_bpermute_b32 v112, v74, v96
	ds_bpermute_b32 v113, v74, v97
	ds_bpermute_b32 v114, v74, v98
	ds_bpermute_b32 v115, v74, v99
	s_waitcnt lgkmcnt(15)
	v_add_f32_e32 v84, v84, v100
	s_waitcnt lgkmcnt(14)
	v_add_f32_e32 v85, v85, v101
	s_waitcnt lgkmcnt(13)
	v_add_f32_e32 v86, v86, v102
	s_waitcnt lgkmcnt(12)
	v_add_f32_e32 v87, v87, v103
	s_waitcnt lgkmcnt(11)
	v_add_f32_e32 v88, v88, v104
	s_waitcnt lgkmcnt(10)
	v_add_f32_e32 v89, v89, v105
	s_waitcnt lgkmcnt(9)
	v_add_f32_e32 v90, v90, v106
	s_waitcnt lgkmcnt(8)
	v_add_f32_e32 v91, v91, v107
	s_waitcnt lgkmcnt(7)
	v_add_f32_e32 v92, v92, v108
	s_waitcnt lgkmcnt(6)
	v_add_f32_e32 v93, v93, v109
	s_waitcnt lgkmcnt(5)
	v_add_f32_e32 v94, v94, v110
	s_waitcnt lgkmcnt(4)
	v_add_f32_e32 v95, v95, v111
	s_waitcnt lgkmcnt(3)
	v_add_f32_e32 v96, v96, v112
	s_waitcnt lgkmcnt(2)
	v_add_f32_e32 v97, v97, v113
	s_waitcnt lgkmcnt(1)
	v_add_f32_e32 v98, v98, v114
	s_waitcnt lgkmcnt(0)
	v_add_f32_e32 v99, v99, v115
	ds_bpermute_b32 v100, v75, v84
	ds_bpermute_b32 v101, v75, v85
	ds_bpermute_b32 v102, v75, v86
	ds_bpermute_b32 v103, v75, v87
	ds_bpermute_b32 v104, v75, v88
	ds_bpermute_b32 v105, v75, v89
	ds_bpermute_b32 v106, v75, v90
	ds_bpermute_b32 v107, v75, v91
	ds_bpermute_b32 v108, v75, v92
	ds_bpermute_b32 v109, v75, v93
	ds_bpermute_b32 v110, v75, v94
	ds_bpermute_b32 v111, v75, v95
	ds_bpermute_b32 v112, v75, v96
	ds_bpermute_b32 v113, v75, v97
	ds_bpermute_b32 v114, v75, v98
	ds_bpermute_b32 v115, v75, v99
	s_waitcnt lgkmcnt(15)
	v_add_f32_e32 v84, v84, v100
	s_waitcnt lgkmcnt(14)
	v_add_f32_e32 v85, v85, v101
	s_waitcnt lgkmcnt(13)
	v_add_f32_e32 v86, v86, v102
	s_waitcnt lgkmcnt(12)
	v_add_f32_e32 v87, v87, v103
	s_waitcnt lgkmcnt(11)
	v_add_f32_e32 v88, v88, v104
	s_waitcnt lgkmcnt(10)
	v_add_f32_e32 v89, v89, v105
	s_waitcnt lgkmcnt(9)
	v_add_f32_e32 v90, v90, v106
	s_waitcnt lgkmcnt(8)
	v_add_f32_e32 v91, v91, v107
	s_waitcnt lgkmcnt(7)
	v_add_f32_e32 v92, v92, v108
	s_waitcnt lgkmcnt(6)
	v_add_f32_e32 v93, v93, v109
	s_waitcnt lgkmcnt(5)
	v_add_f32_e32 v94, v94, v110
	s_waitcnt lgkmcnt(4)
	v_add_f32_e32 v95, v95, v111
	s_waitcnt lgkmcnt(3)
	v_add_f32_e32 v96, v96, v112
	s_waitcnt lgkmcnt(2)
	v_add_f32_e32 v97, v97, v113
	s_waitcnt lgkmcnt(1)
	v_add_f32_e32 v98, v98, v114
	s_waitcnt lgkmcnt(0)
	v_add_f32_e32 v99, v99, v115
	ds_bpermute_b32 v100, v76, v84
	ds_bpermute_b32 v101, v76, v85
	ds_bpermute_b32 v102, v76, v86
	ds_bpermute_b32 v103, v76, v87
	ds_bpermute_b32 v104, v76, v88
	ds_bpermute_b32 v105, v76, v89
	ds_bpermute_b32 v106, v76, v90
	ds_bpermute_b32 v107, v76, v91
	ds_bpermute_b32 v108, v76, v92
	ds_bpermute_b32 v109, v76, v93
	ds_bpermute_b32 v110, v76, v94
	ds_bpermute_b32 v111, v76, v95
	ds_bpermute_b32 v112, v76, v96
	ds_bpermute_b32 v113, v76, v97
	ds_bpermute_b32 v114, v76, v98
	ds_bpermute_b32 v115, v76, v99
	s_waitcnt lgkmcnt(15)
	v_add_f32_e32 v84, v84, v100
	s_waitcnt lgkmcnt(14)
	v_add_f32_e32 v85, v85, v101
	s_waitcnt lgkmcnt(13)
	v_add_f32_e32 v86, v86, v102
	s_waitcnt lgkmcnt(12)
	v_add_f32_e32 v87, v87, v103
	s_waitcnt lgkmcnt(11)
	v_add_f32_e32 v88, v88, v104
	s_waitcnt lgkmcnt(10)
	v_add_f32_e32 v89, v89, v105
	s_waitcnt lgkmcnt(9)
	v_add_f32_e32 v90, v90, v106
	s_waitcnt lgkmcnt(8)
	v_add_f32_e32 v91, v91, v107
	s_waitcnt lgkmcnt(7)
	v_add_f32_e32 v92, v92, v108
	s_waitcnt lgkmcnt(6)
	v_add_f32_e32 v93, v93, v109
	s_waitcnt lgkmcnt(5)
	v_add_f32_e32 v94, v94, v110
	s_waitcnt lgkmcnt(4)
	v_add_f32_e32 v95, v95, v111
	s_waitcnt lgkmcnt(3)
	v_add_f32_e32 v96, v96, v112
	s_waitcnt lgkmcnt(2)
	v_add_f32_e32 v97, v97, v113
	s_waitcnt lgkmcnt(1)
	v_add_f32_e32 v98, v98, v114
	s_waitcnt lgkmcnt(0)
	v_add_f32_e32 v99, v99, v115
	ds_bpermute_b32 v100, v77, v84
	ds_bpermute_b32 v101, v77, v85
	ds_bpermute_b32 v102, v77, v86
	ds_bpermute_b32 v103, v77, v87
	ds_bpermute_b32 v104, v77, v88
	ds_bpermute_b32 v105, v77, v89
	ds_bpermute_b32 v106, v77, v90
	ds_bpermute_b32 v107, v77, v91
	ds_bpermute_b32 v108, v77, v92
	ds_bpermute_b32 v109, v77, v93
	ds_bpermute_b32 v110, v77, v94
	ds_bpermute_b32 v111, v77, v95
	ds_bpermute_b32 v112, v77, v96
	ds_bpermute_b32 v113, v77, v97
	ds_bpermute_b32 v114, v77, v98
	ds_bpermute_b32 v115, v77, v99
	s_waitcnt lgkmcnt(15)
	v_add_f32_e32 v84, v84, v100
	s_waitcnt lgkmcnt(14)
	v_add_f32_e32 v85, v85, v101
	s_waitcnt lgkmcnt(13)
	v_add_f32_e32 v86, v86, v102
	s_waitcnt lgkmcnt(12)
	v_add_f32_e32 v87, v87, v103
	s_waitcnt lgkmcnt(11)
	v_add_f32_e32 v88, v88, v104
	s_waitcnt lgkmcnt(10)
	v_add_f32_e32 v89, v89, v105
	s_waitcnt lgkmcnt(9)
	v_add_f32_e32 v90, v90, v106
	s_waitcnt lgkmcnt(8)
	v_add_f32_e32 v91, v91, v107
	s_waitcnt lgkmcnt(7)
	v_add_f32_e32 v92, v92, v108
	s_waitcnt lgkmcnt(6)
	v_add_f32_e32 v93, v93, v109
	s_waitcnt lgkmcnt(5)
	v_add_f32_e32 v94, v94, v110
	s_waitcnt lgkmcnt(4)
	v_add_f32_e32 v95, v95, v111
	s_waitcnt lgkmcnt(3)
	v_add_f32_e32 v96, v96, v112
	s_waitcnt lgkmcnt(2)
	v_add_f32_e32 v97, v97, v113
	s_waitcnt lgkmcnt(1)
	v_add_f32_e32 v98, v98, v114
	s_waitcnt lgkmcnt(0)
	v_add_f32_e32 v99, v99, v115
	ds_bpermute_b32 v100, v78, v84
	ds_bpermute_b32 v101, v78, v85
	ds_bpermute_b32 v102, v78, v86
	ds_bpermute_b32 v103, v78, v87
	ds_bpermute_b32 v104, v78, v88
	ds_bpermute_b32 v105, v78, v89
	ds_bpermute_b32 v106, v78, v90
	ds_bpermute_b32 v107, v78, v91
	ds_bpermute_b32 v108, v78, v92
	ds_bpermute_b32 v109, v78, v93
	ds_bpermute_b32 v110, v78, v94
	ds_bpermute_b32 v111, v78, v95
	ds_bpermute_b32 v112, v78, v96
	ds_bpermute_b32 v113, v78, v97
	ds_bpermute_b32 v114, v78, v98
	ds_bpermute_b32 v115, v78, v99
	s_waitcnt lgkmcnt(15)
	v_add_f32_e32 v84, v84, v100
	s_waitcnt lgkmcnt(14)
	v_add_f32_e32 v85, v85, v101
	s_waitcnt lgkmcnt(13)
	v_add_f32_e32 v86, v86, v102
	s_waitcnt lgkmcnt(12)
	v_add_f32_e32 v87, v87, v103
	s_waitcnt lgkmcnt(11)
	v_add_f32_e32 v88, v88, v104
	s_waitcnt lgkmcnt(10)
	v_add_f32_e32 v89, v89, v105
	s_waitcnt lgkmcnt(9)
	v_add_f32_e32 v90, v90, v106
	s_waitcnt lgkmcnt(8)
	v_add_f32_e32 v91, v91, v107
	s_waitcnt lgkmcnt(7)
	v_add_f32_e32 v92, v92, v108
	s_waitcnt lgkmcnt(6)
	v_add_f32_e32 v93, v93, v109
	s_waitcnt lgkmcnt(5)
	v_add_f32_e32 v94, v94, v110
	s_waitcnt lgkmcnt(4)
	v_add_f32_e32 v95, v95, v111
	s_waitcnt lgkmcnt(3)
	v_add_f32_e32 v96, v96, v112
	s_waitcnt lgkmcnt(2)
	v_add_f32_e32 v97, v97, v113
	s_waitcnt lgkmcnt(1)
	v_add_f32_e32 v98, v98, v114
	s_waitcnt lgkmcnt(0)
	v_add_f32_e32 v99, v99, v115
	s_mov_b64 exec, 1
	ds_write_b128 v116, v[84:87]
	ds_write_b128 v116, v[88:91] offset:16
	ds_write_b128 v116, v[92:95] offset:32
	ds_write_b128 v116, v[96:99] offset:48
	s_mov_b64 exec, -1
	s_waitcnt lgkmcnt(0)
	s_barrier
	ds_read_b32 v128, v117
	ds_read_b32 v129, v117 offset:64
	ds_read_b32 v130, v117 offset:128
	ds_read_b32 v131, v117 offset:192
	ds_read_b32 v132, v117 offset:256
	ds_read_b32 v133, v117 offset:320
	ds_read_b32 v134, v117 offset:384
	ds_read_b32 v135, v117 offset:448
	s_waitcnt lgkmcnt(0)
	v_add_f32_e32 v128, v128, v129
	v_add_f32_e32 v130, v130, v131
	v_add_f32_e32 v132, v132, v133
	v_add_f32_e32 v134, v134, v135
	v_add_f32_e32 v128, v128, v130
	v_add_f32_e32 v132, v132, v134
	v_add_f32_e32 v128, v128, v132
	v_fmamk_f32 v128, v128, 0x3a000000, v79
	v_cmp_gt_f32_e32 vcc, s33, v128
	v_mul_f32_e32 v118, 0x4f800000, v128
	s_nop 1
	v_cndmask_b32_e32 v128, v128, v118, vcc
	v_sqrt_f32_e32 v118, v128
	s_nop 1
	v_add_u32_e32 v119, -1, v118
	v_fma_f32 v120, -v119, v118, v128
	v_cmp_ge_f32_e64 s[20:21], 0, v120
	v_add_u32_e32 v120, 1, v118
	s_nop 1
	v_cndmask_b32_e64 v119, v118, v119, s[20:21]
	v_fma_f32 v118, -v120, v118, v128
	v_cmp_lt_f32_e64 s[20:21], 0, v118
	s_nop 1
	v_cndmask_b32_e64 v118, v119, v120, s[20:21]
	v_mul_f32_e32 v119, 0x37800000, v118
	v_cndmask_b32_e32 v118, v118, v119, vcc
	v_cmp_class_f32_e32 vcc, v128, v80
	s_nop 1
	v_cndmask_b32_e32 v128, v118, v128, vcc
	v_div_scale_f32 v118, s[22:23], v128, v128, 1.0
	v_rcp_f32_e32 v119, v118
	s_nop 0
	v_fma_f32 v120, -v118, v119, 1.0
	v_fmac_f32_e32 v119, v120, v119
	v_div_scale_f32 v120, vcc, 1.0, v128, 1.0
	v_mul_f32_e32 v121, v120, v119
	v_fma_f32 v122, -v118, v121, v120
	v_fmac_f32_e32 v121, v122, v119
	v_fma_f32 v118, -v118, v121, v120
	v_div_fmas_f32 v118, v118, v119, v121
	v_div_fixup_f32 v118, v118, v128, 1.0
	v_readlane_b32 s12, v118, 0
	v_readlane_b32 s13, v118, 1
	v_readlane_b32 s14, v118, 2
	v_readlane_b32 s15, v118, 3
	v_readlane_b32 s16, v118, 4
	v_readlane_b32 s17, v118, 5
	v_readlane_b32 s18, v118, 6
	v_readlane_b32 s19, v118, 7
	s_nop 1
	v_mul_f32_e32 v4, s12, v4
	v_mul_f32_e32 v5, s12, v5
	v_mul_f32_e32 v6, s12, v6
	v_mul_f32_e32 v7, s12, v7
	v_pk_mul_f32 v[4:5], v[0:1], v[4:5]
	v_pk_mul_f32 v[6:7], v[2:3], v[6:7]
	v_lshl_add_u64 v[126:127], v[70:71], 0, s[24:25]
	global_store_dwordx4 v[126:127], v[4:7], off nt
	s_add_u32 s24, s24, 0x2000
	s_addc_u32 s25, s25, 0
	v_mul_f32_e32 v8, s13, v8
	v_mul_f32_e32 v9, s13, v9
	v_mul_f32_e32 v10, s13, v10
	v_mul_f32_e32 v11, s13, v11
	v_pk_mul_f32 v[8:9], v[0:1], v[8:9]
	v_pk_mul_f32 v[10:11], v[2:3], v[10:11]
	v_lshl_add_u64 v[126:127], v[70:71], 0, s[24:25]
	global_store_dwordx4 v[126:127], v[8:11], off nt
	s_add_u32 s24, s24, 0x2000
	s_addc_u32 s25, s25, 0
	v_mul_f32_e32 v12, s14, v12
	v_mul_f32_e32 v13, s14, v13
	v_mul_f32_e32 v14, s14, v14
	v_mul_f32_e32 v15, s14, v15
	v_pk_mul_f32 v[12:13], v[0:1], v[12:13]
	v_pk_mul_f32 v[14:15], v[2:3], v[14:15]
	v_lshl_add_u64 v[126:127], v[70:71], 0, s[24:25]
	global_store_dwordx4 v[126:127], v[12:15], off nt
	s_add_u32 s24, s24, 0x2000
	s_addc_u32 s25, s25, 0
	v_mul_f32_e32 v16, s15, v16
	v_mul_f32_e32 v17, s15, v17
	v_mul_f32_e32 v18, s15, v18
	v_mul_f32_e32 v19, s15, v19
	v_pk_mul_f32 v[16:17], v[0:1], v[16:17]
	v_pk_mul_f32 v[18:19], v[2:3], v[18:19]
	v_lshl_add_u64 v[126:127], v[70:71], 0, s[24:25]
	global_store_dwordx4 v[126:127], v[16:19], off nt
	s_add_u32 s24, s24, 0x2000
	s_addc_u32 s25, s25, 0
	v_mul_f32_e32 v20, s16, v20
	v_mul_f32_e32 v21, s16, v21
	v_mul_f32_e32 v22, s16, v22
	v_mul_f32_e32 v23, s16, v23
	v_pk_mul_f32 v[20:21], v[0:1], v[20:21]
	v_pk_mul_f32 v[22:23], v[2:3], v[22:23]
	v_lshl_add_u64 v[126:127], v[70:71], 0, s[24:25]
	global_store_dwordx4 v[126:127], v[20:23], off nt
	s_add_u32 s24, s24, 0x2000
	s_addc_u32 s25, s25, 0
	v_mul_f32_e32 v24, s17, v24
	v_mul_f32_e32 v25, s17, v25
	v_mul_f32_e32 v26, s17, v26
	v_mul_f32_e32 v27, s17, v27
	v_pk_mul_f32 v[24:25], v[0:1], v[24:25]
	v_pk_mul_f32 v[26:27], v[2:3], v[26:27]
	v_lshl_add_u64 v[126:127], v[70:71], 0, s[24:25]
	global_store_dwordx4 v[126:127], v[24:27], off nt
	s_add_u32 s24, s24, 0x2000
	s_addc_u32 s25, s25, 0
	v_mul_f32_e32 v28, s18, v28
	v_mul_f32_e32 v29, s18, v29
	v_mul_f32_e32 v30, s18, v30
	v_mul_f32_e32 v31, s18, v31
	v_pk_mul_f32 v[28:29], v[0:1], v[28:29]
	v_pk_mul_f32 v[30:31], v[2:3], v[30:31]
	v_lshl_add_u64 v[126:127], v[70:71], 0, s[24:25]
	global_store_dwordx4 v[126:127], v[28:31], off nt
	s_add_u32 s24, s24, 0x2000
	s_addc_u32 s25, s25, 0
	v_mul_f32_e32 v32, s19, v32
	v_mul_f32_e32 v33, s19, v33
	v_mul_f32_e32 v34, s19, v34
	v_mul_f32_e32 v35, s19, v35
	v_pk_mul_f32 v[32:33], v[0:1], v[32:33]
	v_pk_mul_f32 v[34:35], v[2:3], v[34:35]
	v_lshl_add_u64 v[126:127], v[70:71], 0, s[24:25]
	global_store_dwordx4 v[126:127], v[32:35], off nt
	s_add_u32 s24, s24, 0x2000
	s_addc_u32 s25, s25, 0
	v_readlane_b32 s12, v118, 8
	v_readlane_b32 s13, v118, 9
	v_readlane_b32 s14, v118, 10
	v_readlane_b32 s15, v118, 11
	v_readlane_b32 s16, v118, 12
	v_readlane_b32 s17, v118, 13
	v_readlane_b32 s18, v118, 14
	v_readlane_b32 s19, v118, 15
	s_nop 1
	v_mul_f32_e32 v36, s12, v36
	v_mul_f32_e32 v37, s12, v37
	v_mul_f32_e32 v38, s12, v38
	v_mul_f32_e32 v39, s12, v39
	v_pk_mul_f32 v[36:37], v[0:1], v[36:37]
	v_pk_mul_f32 v[38:39], v[2:3], v[38:39]
	v_lshl_add_u64 v[126:127], v[70:71], 0, s[24:25]
	global_store_dwordx4 v[126:127], v[36:39], off nt
	s_add_u32 s24, s24, 0x2000
	s_addc_u32 s25, s25, 0
	v_mul_f32_e32 v40, s13, v40
	v_mul_f32_e32 v41, s13, v41
	v_mul_f32_e32 v42, s13, v42
	v_mul_f32_e32 v43, s13, v43
	v_pk_mul_f32 v[40:41], v[0:1], v[40:41]
	v_pk_mul_f32 v[42:43], v[2:3], v[42:43]
	v_lshl_add_u64 v[126:127], v[70:71], 0, s[24:25]
	global_store_dwordx4 v[126:127], v[40:43], off nt
	s_add_u32 s24, s24, 0x2000
	s_addc_u32 s25, s25, 0
	v_mul_f32_e32 v44, s14, v44
	v_mul_f32_e32 v45, s14, v45
	v_mul_f32_e32 v46, s14, v46
	v_mul_f32_e32 v47, s14, v47
	v_pk_mul_f32 v[44:45], v[0:1], v[44:45]
	v_pk_mul_f32 v[46:47], v[2:3], v[46:47]
	v_lshl_add_u64 v[126:127], v[70:71], 0, s[24:25]
	global_store_dwordx4 v[126:127], v[44:47], off nt
	s_add_u32 s24, s24, 0x2000
	s_addc_u32 s25, s25, 0
	v_mul_f32_e32 v48, s15, v48
	v_mul_f32_e32 v49, s15, v49
	v_mul_f32_e32 v50, s15, v50
	v_mul_f32_e32 v51, s15, v51
	v_pk_mul_f32 v[48:49], v[0:1], v[48:49]
	v_pk_mul_f32 v[50:51], v[2:3], v[50:51]
	v_lshl_add_u64 v[126:127], v[70:71], 0, s[24:25]
	global_store_dwordx4 v[126:127], v[48:51], off nt
	s_add_u32 s24, s24, 0x2000
	s_addc_u32 s25, s25, 0
	v_mul_f32_e32 v52, s16, v52
	v_mul_f32_e32 v53, s16, v53
	v_mul_f32_e32 v54, s16, v54
	v_mul_f32_e32 v55, s16, v55
	v_pk_mul_f32 v[52:53], v[0:1], v[52:53]
	v_pk_mul_f32 v[54:55], v[2:3], v[54:55]
	v_lshl_add_u64 v[126:127], v[70:71], 0, s[24:25]
	global_store_dwordx4 v[126:127], v[52:55], off nt
	s_add_u32 s24, s24, 0x2000
	s_addc_u32 s25, s25, 0
	v_mul_f32_e32 v56, s17, v56
	v_mul_f32_e32 v57, s17, v57
	v_mul_f32_e32 v58, s17, v58
	v_mul_f32_e32 v59, s17, v59
	v_pk_mul_f32 v[56:57], v[0:1], v[56:57]
	v_pk_mul_f32 v[58:59], v[2:3], v[58:59]
	v_lshl_add_u64 v[126:127], v[70:71], 0, s[24:25]
	global_store_dwordx4 v[126:127], v[56:59], off nt
	s_add_u32 s24, s24, 0x2000
	s_addc_u32 s25, s25, 0
	v_mul_f32_e32 v60, s18, v60
	v_mul_f32_e32 v61, s18, v61
	v_mul_f32_e32 v62, s18, v62
	v_mul_f32_e32 v63, s18, v63
	v_pk_mul_f32 v[60:61], v[0:1], v[60:61]
	v_pk_mul_f32 v[62:63], v[2:3], v[62:63]
	v_lshl_add_u64 v[126:127], v[70:71], 0, s[24:25]
	global_store_dwordx4 v[126:127], v[60:63], off nt
	s_add_u32 s24, s24, 0x2000
	s_addc_u32 s25, s25, 0
	v_mul_f32_e32 v64, s19, v64
	v_mul_f32_e32 v65, s19, v65
	v_mul_f32_e32 v66, s19, v66
	v_mul_f32_e32 v67, s19, v67
	v_pk_mul_f32 v[64:65], v[0:1], v[64:65]
	v_pk_mul_f32 v[66:67], v[2:3], v[66:67]
	v_lshl_add_u64 v[126:127], v[70:71], 0, s[24:25]
	global_store_dwordx4 v[126:127], v[64:67], off nt
	s_add_u32 s24, s24, 0x2000
	s_addc_u32 s25, s25, 0
	s_waitcnt lgkmcnt(0)
	s_barrier
	s_add_i32 s2, s2, s34
	s_add_i32 s4, s4, s88
	s_cmpk_lt_i32 s2, 0x400
	s_cbranch_scc1 .Lnm_fin_loop
	s_branch .LBB0_1382
